# attention inner loop hand-rescheduled (4 tiles/trip, prefetched K/V fragments, imm LDS offsets) + conflict-free K LDS layout
# speedup vs baseline: 1.0381x; 1.0381x over previous
; __device__ __forceinline__ void attn_body(const bf16* __restrict__ Qb, const bf16* __restrict__ Kh, const bf16* __restrict__ Vh, bf16* __restrict__ Ob, int seq, float m0l2, char* lds, bool pre, bool post) {
;     const int tid = tid_fresh(), wid = tid >> 6, lane = tid & 63, r32 = lane & 31, hi = lane >> 5;
;     char* V_lds = lds + OFF_V; char* K_lds = lds + OFF_K;
;     float* li_l = (float*)(lds + OFF_WS) + wid * 64;
;     float l_reg = 0; f32x16 o[2] = {}; bf16x8 qr[4];
;     f32x16 negm;
; #pragma unroll
;     for (int r = 0; r < 16; ++r) negm[r] = -m0l2;
;     asm volatile("" : "+v"(negm));
;     const bf16* Qw = Qb + (long)(wid * QBLK + r32) * LDQ + hi * 8;
; #pragma unroll
;     for (int d0 = 0; d0 < 4; ++d0) qr[d0] = __builtin_nontemporal_load(reinterpret_cast<const bf16x8*>(Qw + d0 * 16));
;     const int wsg = __builtin_amdgcn_readfirstlane(wid);
;     const int oo = (wsg * 64 + lane) * 16;
;     const int ksr = oo >> 8, kcolB = (oo & 255) ^ ((ksr & 15) << 4);
;     const bf16* kptr = Kh + (long)(ksr + 32 * (kcolB >> 7)) * LDK + ((kcolB & 127) >> 1);
;     const int vkk = ((oo >> 9) >> 1) * 8 + ((oo & 511) >> 6), vcc = ((oo >> 9) & 1) * 32 + ((oo & 63) >> 1);
;     const bf16* vptr = Vh + (long)((vkk & ~0xC) | ((vkk & 4) << 1) | ((vkk & 8) >> 1)) * LDK + vcc;
;     LAS unsigned char* const ldsK = (LAS unsigned char*)lds + OFF_K + wsg * 1024; LAS unsigned char* const ldsV = (LAS unsigned char*)lds + OFF_V + wsg * 1024;
;     const int vb0 = (int)(uintptr_t)V_lds + v_rd_base(lane);
;     const int NT = seq / KVBLK;
;     ...
;     f32x16 pA0, pA1, pB0, pB1; bf16x8 pa0, pa1, pa2, pa3;
;     ...
;     if (!pre) { DMA(0); DMA(1); } DMA(2); WBAR(2);
;     qkt(pA0, pA1, K_lds, qr, negm, r32, hi); partialSM(pA0);
; __global__ void __launch_bounds__(NTHR, 2) fwd_kernel(Args A_) {
;     ...
;                     const int u = bx + i * G; if (u >= NB * 16 * 8) break;
;                     const int b = u & 7, rest = u >> 3, h = rest & 7, qb = rest >> 3;
;                     const size_t r0 = (size_t)b * RPB;
;                     const bool more = (u + G < NB * 16 * 8) || hasctx;
;                     att::attn_body(Qb + (r0 + CTXL + qb * 256) * 512 + h * 64, Kb + r0 * 128 + (h >> 2) * 64, Vb + r0 * 128 + (h >> 2) * 64,
;                                    MIXb + (r0 + CTXL + qb * 256) * 1024 + h * 64, RPB, m0l2, (char*)lds, chain && i > 0, chain && more);
.LBB0_24:
	s_and_b32 s27, s6, 7
	s_lshl_b32 s26, s6, 2
	s_mul_i32 s25, s27, 0x1100
	s_and_b32 s11, s26, 0xffffff00
	s_bfe_u32 s7, s6, 0x30003
	s_add_i32 s10, s25, 0x100
	s_ashr_i32 s37, s11, 31
	s_add_u32 s10, s10, s11
	s_addc_u32 s11, 0, s37
	v_mov_b32_e32 v149, v171
	s_lshl_b64 s[38:39], s[10:11], 10
	s_add_u32 s37, s14, s38
	v_ashrrev_i32_e32 v151, 6, v149
	v_and_b32_e32 v150, 31, v149
	v_lshlrev_b32_e32 v128, 5, v151
	s_addc_u32 s39, s15, s39
	s_lshl_b32 s38, s7, 7
	v_or_b32_e32 v16, v128, v150
	s_add_u32 s38, s37, s38
	v_ashrrev_i32_e32 v17, 31, v16
	s_addc_u32 s39, s39, 0
	v_bfe_u32 v152, v149, 5, 1
	v_lshlrev_b64 v[16:17], 10, v[16:17]
	v_mov_b64_e32 v[62:63], v[14:15]
	v_lshl_add_u64 v[16:17], s[38:39], 0, v[16:17]
	v_lshlrev_b32_e32 v130, 4, v152
	v_mov_b32_e32 v131, v161
	v_mov_b64_e32 v[60:61], v[12:13]
	v_mov_b64_e32 v[58:59], v[10:11]
	v_mov_b64_e32 v[56:57], v[8:9]
	v_mov_b64_e32 v[54:55], v[6:7]
	v_mov_b64_e32 v[52:53], v[4:5]
	v_mov_b64_e32 v[50:51], v[2:3]
	v_mov_b64_e32 v[48:49], v[0:1]
	v_lshl_add_u64 v[16:17], v[16:17], 0, v[130:131]
	global_load_dwordx4 v[124:127], v[16:17], off nt
	global_load_dwordx4 v[120:123], v[16:17], off offset:32 nt
	global_load_dwordx4 v[116:119], v[16:17], off offset:64 nt
	global_load_dwordx4 v[112:115], v[16:17], off offset:96 nt
	s_lshl_b32 s25, s25, 8
	s_add_u32 s37, s19, s25
	s_addc_u32 s39, s22, 0
	s_and_b32 s72, s26, 0x80
	s_add_u32 s38, s37, s72
	s_addc_u32 s39, s39, 0
	s_add_u32 s25, s3, s25
	s_addc_u32 s26, s13, 0
	s_add_u32 s46, s25, s72
	s_addc_u32 s47, s26, 0
	s_cmp_lg_u32 s23, 0
	v_and_b32_e32 v131, 63, v149
	v_readfirstlane_b32 s25, v151
	s_cselect_b64 s[50:51], -1, 0
	s_lshl_b32 s25, s25, 10
	v_lshlrev_b32_e32 v38, 4, v131
	v_mov_b32_e32 v17, s25
	v_lshrrev_b32_e32 v18, 4, v17
	v_and_b32_e32 v18, 64, v18
	v_lshrrev_b32_e32 v17, 11, v17
	v_and_b32_e32 v16, 15, v131
	v_lshl_or_b32 v16, v17, 4, v16
	s_nop 0
	v_ashrrev_i32_e32 v17, 31, v16
	v_lshlrev_b64 v[32:33], 8, v[16:17]
	v_lshl_add_u64 v[16:17], s[38:39], 0, v[32:33]
	v_and_or_b32 v160, v131, 48, v18
	v_lshl_add_u64 v[132:133], v[16:17], 0, v[160:161]
	v_lshlrev_b32_e32 v16, 3, v149
	s_ashr_i32 s26, s25, 7
	v_and_b32_e32 v35, 24, v16
	v_lshrrev_b32_e32 v16, 1, v149
	v_bfe_u32 v36, v149, 2, 2
	s_and_b32 s37, s26, -16
	v_and_b32_e32 v37, 8, v16
	s_lshr_b32 s26, s26, 1
	s_and_b32 s38, s26, 4
	v_or3_b32 v16, v37, v36, s37
	v_or_b32_e32 v16, s38, v16
	v_and_b32_e32 v34, 32, v149
	v_ashrrev_i32_e32 v17, 31, v16
	v_or_b32_e32 v18, v35, v34
	v_lshlrev_b64 v[16:17], 8, v[16:17]
	v_lshl_add_u64 v[16:17], s[46:47], 0, v[16:17]
	v_lshlrev_b32_e32 v18, 1, v18
	v_mov_b32_e32 v19, v161
	s_and_b64 s[50:51], s[86:87], s[50:51]
	v_lshl_add_u64 v[134:135], v[16:17], 0, v[18:19]
	s_mov_b64 s[46:47], 0x4000
	s_add_i32 s26, s25, 0
	s_and_b64 vcc, exec, s[50:51]
	v_lshl_add_u64 v[136:137], v[132:133], 0, s[46:47]
	v_lshl_add_u64 v[138:139], v[134:135], 0, s[46:47]
	s_cbranch_vccnz .LBB0_26
	s_add_i32 m0, s26, 0x8000
	s_add_i32 s25, s26, 0xa000
	global_load_lds_dwordx4 v[132:133], off
	s_mov_b32 m0, s26
	s_add_i32 s39, s26, 0x2000
	global_load_lds_dwordx4 v[134:135], off
	s_mov_b32 m0, s25
	s_nop 0
	global_load_lds_dwordx4 v[136:137], off
	s_mov_b32 m0, s39
	s_nop 0
	global_load_lds_dwordx4 v[138:139], off
.LBB0_26:
	s_lshl_b32 s25, s7, 6
	s_cmp_lg_u32 0, -1
	s_cselect_b32 s39, 0, 0
	v_lshl_add_u64 v[16:17], v[132:133], 0, s[82:83]
	s_add_i32 m0, s26, 0xc000
	v_lshlrev_b32_e32 v39, 8, v150
	global_load_lds_dwordx4 v[16:17], off
	v_lshl_add_u64 v[16:17], v[134:135], 0, s[82:83]
	s_add_i32 m0, s26, 0x4000
	s_movk_i32 s7, 0xc0
	global_load_lds_dwordx4 v[16:17], off
	v_lshlrev_b32_e32 v16, 4, v150
	v_and_b32_e32 v80, 0xf0, v16
	v_lshrrev_b32_e32 v39, 4, v150
	v_lshlrev_b32_e32 v39, 11, v39
	v_lshl_add_u32 v39, v130, 4, v39
	v_add_u32_e32 v39, v39, v80
	v_mov_b32_e32 v163, v39
	s_waitcnt vmcnt(2) lgkmcnt(0)
	s_barrier
	v_add_u32_e32 v154, 0, v163
	ds_read_b128 v[40:43], v154 offset:32768
	v_or_b32_e32 v16, 0x80, v130
	v_add_u32_e32 v164, 4096, v39
	v_add_u32_e32 v162, 0, v164
	ds_read_b128 v[44:47], v162 offset:32768
	s_waitcnt vmcnt(0) lgkmcnt(0)
	v_mfma_f32_32x32x16_bf16 v[16:31], v[40:43], v[124:127], v[48:63]
	v_or_b32_e32 v40, 32, v130
	v_add_u32_e32 v165, 512, v39
	v_add_u32_e32 v153, 0, v165
	ds_read_b128 v[40:43], v153 offset:32768
	s_add_i32 s38, s38, s37
	v_mfma_f32_32x32x16_bf16 v[64:79], v[44:47], v[124:127], v[48:63]
	v_or_b32_e32 v44, 0xa0, v130
	v_add_u32_e32 v166, 4608, v39
	v_add_u32_e32 v157, 0, v166
	ds_read_b128 v[44:47], v157 offset:32768
	s_waitcnt lgkmcnt(1)
	v_mfma_f32_32x32x16_bf16 v[16:31], v[40:43], v[120:123], v[16:31]
	v_or_b32_e32 v40, 64, v130
	v_add_u32_e32 v167, 1024, v39
	v_add_u32_e32 v156, 0, v167
	ds_read_b128 v[40:43], v156 offset:32768
	s_waitcnt lgkmcnt(1)
	v_mfma_f32_32x32x16_bf16 v[64:79], v[44:47], v[120:123], v[64:79]
	v_or_b32_e32 v44, 0xc0, v130
	v_add_u32_e32 v168, 5120, v39
	v_add_u32_e32 v158, 0, v168
	ds_read_b128 v[44:47], v158 offset:32768
	s_waitcnt lgkmcnt(1)
	v_mfma_f32_32x32x16_bf16 v[16:31], v[40:43], v[116:119], v[16:31]
	v_or_b32_e32 v40, 0x60, v130
	v_add_u32_e32 v169, 1536, v39
	v_add_u32_e32 v155, 0, v169
	ds_read_b128 v[40:43], v155 offset:32768
	s_waitcnt lgkmcnt(1)
	v_mfma_f32_32x32x16_bf16 v[64:79], v[44:47], v[116:119], v[64:79]
	v_or_b32_e32 v44, 0xe0, v130
	v_add_u32_e32 v170, 5632, v39
	v_add_u32_e32 v159, 0, v170
	ds_read_b128 v[44:47], v159 offset:32768
	v_lshlrev_b32_e32 v39, 1, v131
	v_and_b32_e32 v39, 32, v39
	v_and_or_b32 v38, v38, s7, v39
	s_waitcnt lgkmcnt(1)
; #define PK4(P, BASE, OUT) do { unsigned a0 = cvtpk(P[BASE + 0], P[BASE + 1]), a1 = cvtpk(P[BASE + 2], P[BASE + 3]);   \
;     unsigned b0 = cvtpk(P[BASE + 4], P[BASE + 5]), b1 = cvtpk(P[BASE + 6], P[BASE + 7]);                              \
;     u32x4 w = {a0, a1, b0, b1}; OUT = *reinterpret_cast<bf16x8*>(&w); } while (0)
; #define DMA(t) do { const int t_ = (t) < NT ? (t) : NT - 1; const long off_ = (long)t_ * (KVBLK * LDK); \
;         __builtin_amdgcn_global_load_lds((const unsigned*)(kptr + off_), (LAS unsigned*)(ldsK + SLOT(t)), 16, 0, 0); \
;         __builtin_amdgcn_global_load_lds((const unsigned*)(vptr + off_), (LAS unsigned*)(ldsV + SLOT(t)), 16, 0, 0); } while (0)
; #define WBAR(N) asm volatile("s_waitcnt vmcnt(" #N ") lgkmcnt(0)\n\ts_barrier" ::: "memory")
; #define HALF(PX0, PX1, PY0, PY1, j_, MORE) do { \
;         SBAR(); if (MORE) DMA((j_) + 2); qkt(PX0, PX1, K_lds + SLOT(j_), qr, negm, r32, hi); \
;         finishSM(PY0, PY1, l_reg, pa0, pa1, pa2, pa3); \
;         pv_d0(o, vb0 + SLOT((j_) - 1), pa0, pa1, pa2, pa3); partialSM(PX0); \
;         if (MORE) WBAR(2); else WBAR(0); } while (0)
; __device__ __forceinline__ void partialSM(f32x16& p0) {
; #pragma unroll
;     for (int r = 0; r < 16; ++r) p0[r] = __builtin_amdgcn_exp2f(p0[r]);
; }
; __device__ __forceinline__ void finishSM(f32x16& p0, f32x16& p1, float& l_reg, bf16x8& pa0, bf16x8& pa1, bf16x8& pa2, bf16x8& pa3) {
; #pragma unroll
;     for (int r = 0; r < 16; ++r) p1[r] = __builtin_amdgcn_exp2f(p1[r]);
;     float ps = p0[0];
; #pragma unroll
;     for (int r = 1; r < 16; ++r) ps += p0[r];
; #pragma unroll
;     for (int r = 0; r < 16; ++r) ps += p1[r];
;     l_reg += ps;
;     ...
;     PK4(p0, 0, pa0); PK4(p0, 8, pa1); PK4(p1, 0, pa2); PK4(p1, 8, pa3);
;     ...
; }
; __device__ __forceinline__ void attn_body(const bf16* __restrict__ Qb, const bf16* __restrict__ Kh, const bf16* __restrict__ Vh, bf16* __restrict__ Ob, int seq, float m0l2, char* lds, bool pre, bool post) {
;     ...
;     f32x16 pA0, pA1, pB0, pB1; bf16x8 pa0, pa1, pa2, pa3;
;     ...
;     if (!pre) { DMA(0); DMA(1); } DMA(2); WBAR(2);
;     qkt(pA0, pA1, K_lds, qr, negm, r32, hi); partialSM(pA0);
;     int j = 1;
;     for (; j + 4 < NT; j += 2) {
;         HALF(pB0, pB1, pA0, pA1, j, true);
;         HALF(pA0, pA1, pB0, pB1, j + 1, true);
	v_mfma_f32_32x32x16_bf16 v[16:31], v[40:43], v[112:115], v[16:31]
	v_lshlrev_b32_e32 v39, 5, v131
	v_and_b32_e32 v39, 0x400, v39
	v_or3_b32 v129, v38, v39, v35
	v_add_u32_e32 v172, s39, v129
	s_mov_b32 s7, -1
	s_nop 6
	v_exp_f32_e32 v183, v16
	s_waitcnt lgkmcnt(0)
	v_mfma_f32_32x32x16_bf16 v[64:79], v[44:47], v[112:115], v[64:79]
	v_exp_f32_e32 v188, v17
	v_mad_u64_u32 v[16:17], s[46:47], s27, v211, v[32:33]
	v_lshl_add_u64 v[16:17], v[16:17], 0, v[160:161]
	v_lshl_add_u64 v[140:141], s[28:29], 0, v[16:17]
	v_add3_u32 v16, s38, v37, v36
	v_ashrrev_i32_e32 v17, 31, v16
	v_exp_f32_e32 v185, v18
	v_exp_f32_e32 v187, v19
	v_exp_f32_e32 v184, v20
	v_exp_f32_e32 v186, v21
	v_exp_f32_e32 v181, v22
	v_exp_f32_e32 v182, v23
	v_exp_f32_e32 v178, v24
	v_exp_f32_e32 v180, v25
	v_exp_f32_e32 v176, v26
	v_exp_f32_e32 v179, v27
	v_exp_f32_e32 v175, v28
	v_exp_f32_e32 v177, v29
	v_exp_f32_e32 v173, v30
	v_exp_f32_e32 v174, v31
	v_lshlrev_b64 v[16:17], 8, v[16:17]
	v_mad_u64_u32 v[16:17], s[38:39], s27, v211, v[16:17]
	v_add_u32_e32 v18, v34, v35
	v_lshl_or_b32 v16, v18, 1, v16
	v_mov_b32_e32 v160, 0
	v_lshl_add_u64 v[142:143], s[28:29], 0, v[16:17]
	s_mov_b32 s27, 0x8000
	v_mov_b32_e32 v16, 0
	v_mov_b32_e32 v17, v160
	v_mov_b32_e32 v18, v160
	v_mov_b32_e32 v19, v160
	v_mov_b32_e32 v20, v160
	v_mov_b32_e32 v21, v160
	v_mov_b32_e32 v22, v160
	v_mov_b32_e32 v23, v160
	v_mov_b32_e32 v24, v160
	v_mov_b32_e32 v25, v160
	v_mov_b32_e32 v26, v160
	v_mov_b32_e32 v27, v160
	v_mov_b32_e32 v28, v160
	v_mov_b32_e32 v29, v160
	v_mov_b32_e32 v30, v160
	v_mov_b32_e32 v31, v160
	v_mov_b32_e32 v32, 0
	v_mov_b32_e32 v33, v160
	v_mov_b32_e32 v34, v160
	v_mov_b32_e32 v35, v160
	v_mov_b32_e32 v36, v160
	v_mov_b32_e32 v37, v160
	v_mov_b32_e32 v38, v160
	v_mov_b32_e32 v39, v160
	v_mov_b32_e32 v40, v160
	v_mov_b32_e32 v41, v160
	v_mov_b32_e32 v42, v160
	v_mov_b32_e32 v43, v160
	v_mov_b32_e32 v44, v160
	v_mov_b32_e32 v45, v160
	v_mov_b32_e32 v46, v160
	v_mov_b32_e32 v47, v160
	v_lshl_add_u64 v[140:141], v[140:141], 0, s[72:73]
	v_lshl_add_u64 v[142:143], v[142:143], 0, s[72:73]
	s_mov_b64 s[38:39], 0x10e06000
	s_mov_b64 s[46:47], 0x11686000
	s_mov_b64 s[62:63], 0x4000
	v_lshl_add_u64 v[140:141], v[140:141], 0, s[38:39]
	v_lshl_add_u64 v[142:143], v[142:143], 0, s[46:47]
	ds_read_b128 v[234:237], v163 offset:40960
	ds_read_b128 v[238:241], v165 offset:40960
	ds_read_b128 v[242:245], v167 offset:40960
	ds_read_b128 v[246:249], v169 offset:40960
.LBB0_27:
	s_add_i32 m0, s26, 0xe000
	s_nop 0
	global_load_lds_dwordx4 v[140:141], off
	s_add_i32 m0, s26, 0x6000
	v_lshl_add_u64 v[140:141], v[140:141], 0, s[62:63]
	global_load_lds_dwordx4 v[142:143], off
	v_lshl_add_u64 v[142:143], v[142:143], 0, s[62:63]
	s_waitcnt lgkmcnt(3)
	v_mfma_f32_32x32x16_bf16 v[96:111], v[234:237], v[124:127], v[0:15]
	ds_read_b64_tr_b16 v[190:191], v172 offset:0
	ds_read_b64_tr_b16 v[192:193], v172 offset:256
	v_add_f32_e32 v189, v183, v188
	v_add_f32_e32 v189, v185, v189
	v_add_f32_e32 v189, v187, v189
	v_add_f32_e32 v189, v184, v189
	v_exp_f32_e32 v64, v64
	s_waitcnt lgkmcnt(4)
	v_mfma_f32_32x32x16_bf16 v[96:111], v[238:241], v[120:123], v[96:111]
	ds_read_b64_tr_b16 v[194:195], v172 offset:2048
	ds_read_b64_tr_b16 v[196:197], v172 offset:2304
	v_exp_f32_e32 v65, v65
	v_cvt_pk_bf16_f32 v48, v183, v188
	v_exp_f32_e32 v66, v66
	v_exp_f32_e32 v67, v67
	s_waitcnt lgkmcnt(5)
	v_mfma_f32_32x32x16_bf16 v[96:111], v[242:245], v[116:119], v[96:111]
	ds_read_b64_tr_b16 v[144:145], v172 offset:4096
	ds_read_b64_tr_b16 v[146:147], v172 offset:4352
	v_cvt_pk_bf16_f32 v49, v185, v187
	v_exp_f32_e32 v68, v68
	v_exp_f32_e32 v69, v69
	v_cvt_pk_bf16_f32 v50, v184, v186
	s_waitcnt lgkmcnt(6)
	v_mfma_f32_32x32x16_bf16 v[96:111], v[246:249], v[112:115], v[96:111]
	ds_read_b64_tr_b16 v[250:251], v172 offset:6144
	ds_read_b64_tr_b16 v[252:253], v172 offset:6400
	v_exp_f32_e32 v70, v70
	v_exp_f32_e32 v71, v71
	v_cvt_pk_bf16_f32 v51, v181, v182
	v_cvt_pk_bf16_f32 v52, v178, v180
	s_waitcnt lgkmcnt(6)
	v_mfma_f32_32x32x16_bf16 v[32:47], v[48:51], v[190:193], v[32:47]
	ds_read_b64_tr_b16 v[190:191], v172 offset:512
	ds_read_b64_tr_b16 v[192:193], v172 offset:768
	ds_read_b128 v[234:237], v164 offset:40960
	v_cvt_pk_bf16_f32 v53, v176, v179
	v_cvt_pk_bf16_f32 v54, v175, v177
	v_cvt_pk_bf16_f32 v55, v173, v174
	v_cvt_pk_bf16_f32 v56, v64, v65
	v_cvt_pk_bf16_f32 v57, v66, v67
	v_exp_f32_e32 v72, v72
	s_waitcnt lgkmcnt(7)
	v_mfma_f32_32x32x16_bf16 v[32:47], v[52:55], v[194:197], v[32:47]
	ds_read_b64_tr_b16 v[194:195], v172 offset:2560
	ds_read_b64_tr_b16 v[196:197], v172 offset:2816
	ds_read_b128 v[238:241], v166 offset:40960
	v_cvt_pk_bf16_f32 v58, v68, v69
	v_cvt_pk_bf16_f32 v59, v70, v71
	v_exp_f32_e32 v73, v73
	v_exp_f32_e32 v74, v74
	s_waitcnt lgkmcnt(4)
	v_mfma_f32_32x32x16_bf16 v[16:31], v[48:51], v[190:193], v[16:31]
	ds_read_b64_tr_b16 v[190:191], v172 offset:4608
	ds_read_b64_tr_b16 v[192:193], v172 offset:4864
	ds_read_b128 v[242:245], v168 offset:40960
	v_exp_f32_e32 v75, v75
	v_exp_f32_e32 v76, v76
	v_exp_f32_e32 v77, v77
	v_add_f32_e32 v189, v186, v189
	s_waitcnt lgkmcnt(4)
	v_mfma_f32_32x32x16_bf16 v[16:31], v[52:55], v[194:197], v[16:31]
	ds_read_b64_tr_b16 v[194:195], v172 offset:6656
	ds_read_b64_tr_b16 v[196:197], v172 offset:6912
	ds_read_b128 v[246:249], v170 offset:40960
	v_exp_f32_e32 v78, v78
	v_exp_f32_e32 v79, v79
	v_add_f32_e32 v189, v181, v189
	v_add_f32_e32 v189, v182, v189
	v_cvt_pk_bf16_f32 v60, v72, v73
	v_mfma_f32_32x32x16_bf16 v[32:47], v[56:59], v[144:147], v[32:47]
	v_cvt_pk_bf16_f32 v61, v74, v75
	v_cvt_pk_bf16_f32 v62, v76, v77
	v_cvt_pk_bf16_f32 v63, v78, v79
	v_add_f32_e32 v189, v178, v189
	v_add_f32_e32 v189, v180, v189
	v_add_f32_e32 v189, v176, v189
	v_add_f32_e32 v189, v179, v189
	v_mfma_f32_32x32x16_bf16 v[32:47], v[60:63], v[250:253], v[32:47]
	v_exp_f32_e32 v96, v96
	v_exp_f32_e32 v97, v97
	v_add_f32_e32 v189, v175, v189
	v_add_f32_e32 v189, v177, v189
	v_add_f32_e32 v189, v173, v189
	s_waitcnt lgkmcnt(4)
	v_mfma_f32_32x32x16_bf16 v[16:31], v[56:59], v[190:193], v[16:31]
	v_exp_f32_e32 v98, v98
	v_exp_f32_e32 v99, v99
	v_add_f32_e32 v189, v174, v189
	v_add_f32_e32 v189, v64, v189
	v_add_f32_e32 v189, v65, v189
	s_waitcnt lgkmcnt(1)
	v_mfma_f32_32x32x16_bf16 v[16:31], v[60:63], v[194:197], v[16:31]
	v_exp_f32_e32 v100, v100
	v_exp_f32_e32 v101, v101
	v_add_f32_e32 v189, v66, v189
	v_add_f32_e32 v189, v67, v189
	v_add_f32_e32 v189, v68, v189
	s_waitcnt vmcnt(2) lgkmcnt(0)
	s_barrier
; #define LAS __attribute__((address_space(3)))
; __device__ __forceinline__ void qkt(f32x16& p0, f32x16& p1, const char* Ks, const bf16x8* qr, const f32x16& negm, int r32, int hi) {
; #pragma unroll
;     for (int d0 = 0; d0 < 4; ++d0) { const int cb = (d0 * 16 + hi * 8) * 2;
;         const bf16x8 b0 = *reinterpret_cast<const bf16x8*>(Ks + KSWZ(r32, cb));
;         const bf16x8 b1 = *reinterpret_cast<const bf16x8*>(Ks + KSWZ(r32, 128 + cb));
;         if (d0 == 0) { p0 = __builtin_amdgcn_mfma_f32_32x32x16_bf16(b0, qr[0], negm, 0, 0, 0); p1 = __builtin_amdgcn_mfma_f32_32x32x16_bf16(b1, qr[0], negm, 0, 0, 0); }
;         else { p0 = __builtin_amdgcn_mfma_f32_32x32x16_bf16(b0, qr[d0], p0, 0, 0, 0); p1 = __builtin_amdgcn_mfma_f32_32x32x16_bf16(b1, qr[d0], p1, 0, 0, 0); } }
; }
; __device__ __forceinline__ int v_st(int k, int c) { const int kk = (k & ~0xC) | ((k & 4) << 1) | ((k & 8) >> 1); return ((kk >> 3) * 2 + (c >> 5)) * 512 + ((kk & 7) * 32 + (c & 31)) * 2; }
; __device__ __forceinline__ int v_rd_base(int lane) { return (((lane & 3) << 3) | (((lane >> 2) & 3) << 6) | (((lane >> 4) & 1) << 5)) + ((lane >> 5) & 1) * 1024; }
; template <int OFF> __device__ __forceinline__ s16x4 tr_read(int vb) {
;     return __builtin_bit_cast(s16x4, __builtin_amdgcn_ds_read_tr16_b64_v4i16((LAS v4i16_t*)(unsigned)(vb + OFF)));
; }
; template <int D0> __device__ __forceinline__ void pv_one(f32x16& od, int vb, bf16x8 pa0, bf16x8 pa1, bf16x8 pa2, bf16x8 pa3) {
;     const s16x4 l0 = tr_read<v_rd_off(D0, 0, 0)>(vb), h0 = tr_read<v_rd_off(D0, 0, 1)>(vb), l1 = tr_read<v_rd_off(D0, 1, 0)>(vb), h1 = tr_read<v_rd_off(D0, 1, 1)>(vb);
;     const s16x4 l2 = tr_read<v_rd_off(D0, 2, 0)>(vb), h2 = tr_read<v_rd_off(D0, 2, 1)>(vb), l3 = tr_read<v_rd_off(D0, 3, 0)>(vb), h3 = tr_read<v_rd_off(D0, 3, 1)>(vb);
;     ...
;     od = __builtin_amdgcn_mfma_f32_32x32x16_bf16(pa0, PK(l0, h0), od, 0, 0, 0);
;     od = __builtin_amdgcn_mfma_f32_32x32x16_bf16(pa1, PK(l1, h1), od, 0, 0, 0);
;     od = __builtin_amdgcn_mfma_f32_32x32x16_bf16(pa2, PK(l2, h2), od, 0, 0, 0);
;     od = __builtin_amdgcn_mfma_f32_32x32x16_bf16(pa3, PK(l3, h3), od, 0, 0, 0);
;     ...
; }
	v_mfma_f32_32x32x16_bf16 v[80:95], v[234:237], v[124:127], v[0:15]
	ds_read_b128 v[234:237], v163 offset:49152
	v_exp_f32_e32 v102, v102
	v_exp_f32_e32 v103, v103
	v_add_f32_e32 v189, v69, v189
	v_add_f32_e32 v189, v70, v189
	v_add_f32_e32 v189, v71, v189
	v_mfma_f32_32x32x16_bf16 v[80:95], v[238:241], v[120:123], v[80:95]
	ds_read_b128 v[238:241], v165 offset:49152
	v_exp_f32_e32 v104, v104
	v_exp_f32_e32 v105, v105
	v_exp_f32_e32 v106, v106
	v_add_f32_e32 v189, v72, v189
	v_add_f32_e32 v189, v73, v189
	v_mfma_f32_32x32x16_bf16 v[80:95], v[242:245], v[116:119], v[80:95]
	ds_read_b128 v[242:245], v167 offset:49152
	v_exp_f32_e32 v107, v107
	v_exp_f32_e32 v108, v108
	v_exp_f32_e32 v109, v109
	v_add_f32_e32 v189, v74, v189
	v_add_f32_e32 v189, v75, v189
	v_mfma_f32_32x32x16_bf16 v[80:95], v[246:249], v[112:115], v[80:95]
	ds_read_b128 v[246:249], v169 offset:49152
	v_exp_f32_e32 v110, v110
	v_exp_f32_e32 v111, v111
	v_add_f32_e32 v189, v76, v189
	v_add_f32_e32 v189, v77, v189
	v_add_f32_e32 v189, v78, v189
	v_add_f32_e32 v189, v79, v189
	v_add_f32_e32 v160, v160, v189
	s_add_i32 m0, s26, 0x8000
	s_nop 0
	global_load_lds_dwordx4 v[140:141], off
	s_mov_b32 m0, s26
	v_lshl_add_u64 v[140:141], v[140:141], 0, s[62:63]
	global_load_lds_dwordx4 v[142:143], off
	v_lshl_add_u64 v[142:143], v[142:143], 0, s[62:63]
	s_waitcnt lgkmcnt(3)
	v_mfma_f32_32x32x16_bf16 v[218:233], v[234:237], v[124:127], v[0:15]
	ds_read_b64_tr_b16 v[190:191], v172 offset:8192
	ds_read_b64_tr_b16 v[192:193], v172 offset:8448
	v_add_f32_e32 v189, v96, v97
	v_add_f32_e32 v189, v98, v189
	v_add_f32_e32 v189, v99, v189
	v_add_f32_e32 v189, v100, v189
	v_exp_f32_e32 v80, v80
	s_waitcnt lgkmcnt(4)
	v_mfma_f32_32x32x16_bf16 v[218:233], v[238:241], v[120:123], v[218:233]
	ds_read_b64_tr_b16 v[194:195], v172 offset:10240
	ds_read_b64_tr_b16 v[196:197], v172 offset:10496
	v_exp_f32_e32 v81, v81
	v_cvt_pk_bf16_f32 v48, v96, v97
	v_exp_f32_e32 v82, v82
	v_exp_f32_e32 v83, v83
	s_waitcnt lgkmcnt(5)
	v_mfma_f32_32x32x16_bf16 v[218:233], v[242:245], v[116:119], v[218:233]
	ds_read_b64_tr_b16 v[144:145], v172 offset:12288
	ds_read_b64_tr_b16 v[146:147], v172 offset:12544
	v_cvt_pk_bf16_f32 v49, v98, v99
	v_exp_f32_e32 v84, v84
	v_exp_f32_e32 v85, v85
	v_cvt_pk_bf16_f32 v50, v100, v101
	s_waitcnt lgkmcnt(6)
	v_mfma_f32_32x32x16_bf16 v[218:233], v[246:249], v[112:115], v[218:233]
	ds_read_b64_tr_b16 v[250:251], v172 offset:14336
	ds_read_b64_tr_b16 v[252:253], v172 offset:14592
	v_exp_f32_e32 v86, v86
	v_exp_f32_e32 v87, v87
	v_cvt_pk_bf16_f32 v51, v102, v103
	v_cvt_pk_bf16_f32 v52, v104, v105
	s_waitcnt lgkmcnt(6)
	v_mfma_f32_32x32x16_bf16 v[32:47], v[48:51], v[190:193], v[32:47]
	ds_read_b64_tr_b16 v[190:191], v172 offset:8704
	ds_read_b64_tr_b16 v[192:193], v172 offset:8960
	ds_read_b128 v[234:237], v164 offset:49152
	v_cvt_pk_bf16_f32 v53, v106, v107
	v_cvt_pk_bf16_f32 v54, v108, v109
	v_cvt_pk_bf16_f32 v55, v110, v111
	v_cvt_pk_bf16_f32 v56, v80, v81
	v_cvt_pk_bf16_f32 v57, v82, v83
	v_exp_f32_e32 v88, v88
	s_waitcnt lgkmcnt(7)
	v_mfma_f32_32x32x16_bf16 v[32:47], v[52:55], v[194:197], v[32:47]
	ds_read_b64_tr_b16 v[194:195], v172 offset:10752
	ds_read_b64_tr_b16 v[196:197], v172 offset:11008
	ds_read_b128 v[238:241], v166 offset:49152
	v_cvt_pk_bf16_f32 v58, v84, v85
	v_cvt_pk_bf16_f32 v59, v86, v87
	v_exp_f32_e32 v89, v89
	v_exp_f32_e32 v90, v90
	s_waitcnt lgkmcnt(4)
	v_mfma_f32_32x32x16_bf16 v[16:31], v[48:51], v[190:193], v[16:31]
	ds_read_b64_tr_b16 v[190:191], v172 offset:12800
	ds_read_b64_tr_b16 v[192:193], v172 offset:13056
	ds_read_b128 v[242:245], v168 offset:49152
	v_exp_f32_e32 v91, v91
	v_exp_f32_e32 v92, v92
	v_exp_f32_e32 v93, v93
	v_add_f32_e32 v189, v101, v189
	s_waitcnt lgkmcnt(4)
	v_mfma_f32_32x32x16_bf16 v[16:31], v[52:55], v[194:197], v[16:31]
	ds_read_b64_tr_b16 v[194:195], v172 offset:14848
	ds_read_b64_tr_b16 v[196:197], v172 offset:15104
	ds_read_b128 v[246:249], v170 offset:49152
	v_exp_f32_e32 v94, v94
	v_exp_f32_e32 v95, v95
	v_add_f32_e32 v189, v102, v189
	v_add_f32_e32 v189, v103, v189
	v_cvt_pk_bf16_f32 v60, v88, v89
	v_mfma_f32_32x32x16_bf16 v[32:47], v[56:59], v[144:147], v[32:47]
	v_cvt_pk_bf16_f32 v61, v90, v91
	v_cvt_pk_bf16_f32 v62, v92, v93
	v_cvt_pk_bf16_f32 v63, v94, v95
	v_add_f32_e32 v189, v104, v189
	v_add_f32_e32 v189, v105, v189
	v_add_f32_e32 v189, v106, v189
	v_add_f32_e32 v189, v107, v189
	v_mfma_f32_32x32x16_bf16 v[32:47], v[60:63], v[250:253], v[32:47]
	v_exp_f32_e32 v183, v218
	v_exp_f32_e32 v188, v219
	v_add_f32_e32 v189, v108, v189
	v_add_f32_e32 v189, v109, v189
	v_add_f32_e32 v189, v110, v189
	s_waitcnt lgkmcnt(4)
	v_mfma_f32_32x32x16_bf16 v[16:31], v[56:59], v[190:193], v[16:31]
	v_exp_f32_e32 v185, v220
	v_exp_f32_e32 v187, v221
	v_add_f32_e32 v189, v111, v189
	v_add_f32_e32 v189, v80, v189
	v_add_f32_e32 v189, v81, v189
	s_waitcnt lgkmcnt(1)
	v_mfma_f32_32x32x16_bf16 v[16:31], v[60:63], v[194:197], v[16:31]
	v_exp_f32_e32 v184, v222
	v_exp_f32_e32 v186, v223
	v_add_f32_e32 v189, v82, v189
	v_add_f32_e32 v189, v83, v189
	v_add_f32_e32 v189, v84, v189
	s_waitcnt vmcnt(2) lgkmcnt(0)
	s_barrier
; #define LAS __attribute__((address_space(3)))
; __device__ __forceinline__ void qkt(f32x16& p0, f32x16& p1, const char* Ks, const bf16x8* qr, const f32x16& negm, int r32, int hi) {
; #pragma unroll
;     for (int d0 = 0; d0 < 4; ++d0) { const int cb = (d0 * 16 + hi * 8) * 2;
;         const bf16x8 b0 = *reinterpret_cast<const bf16x8*>(Ks + KSWZ(r32, cb));
;         const bf16x8 b1 = *reinterpret_cast<const bf16x8*>(Ks + KSWZ(r32, 128 + cb));
;         if (d0 == 0) { p0 = __builtin_amdgcn_mfma_f32_32x32x16_bf16(b0, qr[0], negm, 0, 0, 0); p1 = __builtin_amdgcn_mfma_f32_32x32x16_bf16(b1, qr[0], negm, 0, 0, 0); }
;         else { p0 = __builtin_amdgcn_mfma_f32_32x32x16_bf16(b0, qr[d0], p0, 0, 0, 0); p1 = __builtin_amdgcn_mfma_f32_32x32x16_bf16(b1, qr[d0], p1, 0, 0, 0); } }
; }
; __device__ __forceinline__ int v_st(int k, int c) { const int kk = (k & ~0xC) | ((k & 4) << 1) | ((k & 8) >> 1); return ((kk >> 3) * 2 + (c >> 5)) * 512 + ((kk & 7) * 32 + (c & 31)) * 2; }
; __device__ __forceinline__ int v_rd_base(int lane) { return (((lane & 3) << 3) | (((lane >> 2) & 3) << 6) | (((lane >> 4) & 1) << 5)) + ((lane >> 5) & 1) * 1024; }
; template <int OFF> __device__ __forceinline__ s16x4 tr_read(int vb) {
;     return __builtin_bit_cast(s16x4, __builtin_amdgcn_ds_read_tr16_b64_v4i16((LAS v4i16_t*)(unsigned)(vb + OFF)));
; }
; template <int D0> __device__ __forceinline__ void pv_one(f32x16& od, int vb, bf16x8 pa0, bf16x8 pa1, bf16x8 pa2, bf16x8 pa3) {
;     const s16x4 l0 = tr_read<v_rd_off(D0, 0, 0)>(vb), h0 = tr_read<v_rd_off(D0, 0, 1)>(vb), l1 = tr_read<v_rd_off(D0, 1, 0)>(vb), h1 = tr_read<v_rd_off(D0, 1, 1)>(vb);
;     const s16x4 l2 = tr_read<v_rd_off(D0, 2, 0)>(vb), h2 = tr_read<v_rd_off(D0, 2, 1)>(vb), l3 = tr_read<v_rd_off(D0, 3, 0)>(vb), h3 = tr_read<v_rd_off(D0, 3, 1)>(vb);
;     ...
;     od = __builtin_amdgcn_mfma_f32_32x32x16_bf16(pa0, PK(l0, h0), od, 0, 0, 0);
;     od = __builtin_amdgcn_mfma_f32_32x32x16_bf16(pa1, PK(l1, h1), od, 0, 0, 0);
;     od = __builtin_amdgcn_mfma_f32_32x32x16_bf16(pa2, PK(l2, h2), od, 0, 0, 0);
;     od = __builtin_amdgcn_mfma_f32_32x32x16_bf16(pa3, PK(l3, h3), od, 0, 0, 0);
;     ...
; }
	v_mfma_f32_32x32x16_bf16 v[64:79], v[234:237], v[124:127], v[0:15]
	ds_read_b128 v[234:237], v163 offset:57344
	v_exp_f32_e32 v181, v224
	v_exp_f32_e32 v182, v225
	v_add_f32_e32 v189, v85, v189
	v_add_f32_e32 v189, v86, v189
	v_add_f32_e32 v189, v87, v189
	v_mfma_f32_32x32x16_bf16 v[64:79], v[238:241], v[120:123], v[64:79]
	ds_read_b128 v[238:241], v165 offset:57344
	v_exp_f32_e32 v178, v226
	v_exp_f32_e32 v180, v227
	v_exp_f32_e32 v176, v228
	v_add_f32_e32 v189, v88, v189
	v_add_f32_e32 v189, v89, v189
	v_mfma_f32_32x32x16_bf16 v[64:79], v[242:245], v[116:119], v[64:79]
	ds_read_b128 v[242:245], v167 offset:57344
	v_exp_f32_e32 v179, v229
	v_exp_f32_e32 v175, v230
	v_exp_f32_e32 v177, v231
	v_add_f32_e32 v189, v90, v189
	v_add_f32_e32 v189, v91, v189
	v_mfma_f32_32x32x16_bf16 v[64:79], v[246:249], v[112:115], v[64:79]
	ds_read_b128 v[246:249], v169 offset:57344
	v_exp_f32_e32 v173, v232
	v_exp_f32_e32 v174, v233
	v_add_f32_e32 v189, v92, v189
	v_add_f32_e32 v189, v93, v189
	v_add_f32_e32 v189, v94, v189
	v_add_f32_e32 v189, v95, v189
	v_add_f32_e32 v160, v160, v189
	s_add_i32 m0, s26, 0xa000
	s_nop 0
	global_load_lds_dwordx4 v[140:141], off
	s_add_i32 m0, s26, 0x2000
	v_lshl_add_u64 v[140:141], v[140:141], 0, s[62:63]
	global_load_lds_dwordx4 v[142:143], off
	v_lshl_add_u64 v[142:143], v[142:143], 0, s[62:63]
	s_waitcnt lgkmcnt(3)
	v_mfma_f32_32x32x16_bf16 v[96:111], v[234:237], v[124:127], v[0:15]
	ds_read_b64_tr_b16 v[190:191], v172 offset:16384
	ds_read_b64_tr_b16 v[192:193], v172 offset:16640
	v_add_f32_e32 v189, v183, v188
	v_add_f32_e32 v189, v185, v189
	v_add_f32_e32 v189, v187, v189
	v_add_f32_e32 v189, v184, v189
	v_exp_f32_e32 v64, v64
	s_waitcnt lgkmcnt(4)
	v_mfma_f32_32x32x16_bf16 v[96:111], v[238:241], v[120:123], v[96:111]
	ds_read_b64_tr_b16 v[194:195], v172 offset:18432
	ds_read_b64_tr_b16 v[196:197], v172 offset:18688
	v_exp_f32_e32 v65, v65
	v_cvt_pk_bf16_f32 v48, v183, v188
	v_exp_f32_e32 v66, v66
	v_exp_f32_e32 v67, v67
	s_waitcnt lgkmcnt(5)
	v_mfma_f32_32x32x16_bf16 v[96:111], v[242:245], v[116:119], v[96:111]
	ds_read_b64_tr_b16 v[144:145], v172 offset:20480
	ds_read_b64_tr_b16 v[146:147], v172 offset:20736
	v_cvt_pk_bf16_f32 v49, v185, v187
	v_exp_f32_e32 v68, v68
	v_exp_f32_e32 v69, v69
	v_cvt_pk_bf16_f32 v50, v184, v186
	s_waitcnt lgkmcnt(6)
	v_mfma_f32_32x32x16_bf16 v[96:111], v[246:249], v[112:115], v[96:111]
	ds_read_b64_tr_b16 v[250:251], v172 offset:22528
	ds_read_b64_tr_b16 v[252:253], v172 offset:22784
	v_exp_f32_e32 v70, v70
	v_exp_f32_e32 v71, v71
	v_cvt_pk_bf16_f32 v51, v181, v182
	v_cvt_pk_bf16_f32 v52, v178, v180
	s_waitcnt lgkmcnt(6)
	v_mfma_f32_32x32x16_bf16 v[32:47], v[48:51], v[190:193], v[32:47]
	ds_read_b64_tr_b16 v[190:191], v172 offset:16896
	ds_read_b64_tr_b16 v[192:193], v172 offset:17152
	ds_read_b128 v[234:237], v164 offset:57344
	v_cvt_pk_bf16_f32 v53, v176, v179
	v_cvt_pk_bf16_f32 v54, v175, v177
	v_cvt_pk_bf16_f32 v55, v173, v174
	v_cvt_pk_bf16_f32 v56, v64, v65
	v_cvt_pk_bf16_f32 v57, v66, v67
	v_exp_f32_e32 v72, v72
	s_waitcnt lgkmcnt(7)
	v_mfma_f32_32x32x16_bf16 v[32:47], v[52:55], v[194:197], v[32:47]
	ds_read_b64_tr_b16 v[194:195], v172 offset:18944
	ds_read_b64_tr_b16 v[196:197], v172 offset:19200
	ds_read_b128 v[238:241], v166 offset:57344
	v_cvt_pk_bf16_f32 v58, v68, v69
	v_cvt_pk_bf16_f32 v59, v70, v71
	v_exp_f32_e32 v73, v73
	v_exp_f32_e32 v74, v74
	s_waitcnt lgkmcnt(4)
	v_mfma_f32_32x32x16_bf16 v[16:31], v[48:51], v[190:193], v[16:31]
	ds_read_b64_tr_b16 v[190:191], v172 offset:20992
	ds_read_b64_tr_b16 v[192:193], v172 offset:21248
	ds_read_b128 v[242:245], v168 offset:57344
	v_exp_f32_e32 v75, v75
	v_exp_f32_e32 v76, v76
	v_exp_f32_e32 v77, v77
	v_add_f32_e32 v189, v186, v189
	s_waitcnt lgkmcnt(4)
	v_mfma_f32_32x32x16_bf16 v[16:31], v[52:55], v[194:197], v[16:31]
	ds_read_b64_tr_b16 v[194:195], v172 offset:23040
	ds_read_b64_tr_b16 v[196:197], v172 offset:23296
	ds_read_b128 v[246:249], v170 offset:57344
	v_exp_f32_e32 v78, v78
	v_exp_f32_e32 v79, v79
	v_add_f32_e32 v189, v181, v189
	v_add_f32_e32 v189, v182, v189
	v_cvt_pk_bf16_f32 v60, v72, v73
	v_mfma_f32_32x32x16_bf16 v[32:47], v[56:59], v[144:147], v[32:47]
	v_cvt_pk_bf16_f32 v61, v74, v75
	v_cvt_pk_bf16_f32 v62, v76, v77
	v_cvt_pk_bf16_f32 v63, v78, v79
	v_add_f32_e32 v189, v178, v189
	v_add_f32_e32 v189, v180, v189
	v_add_f32_e32 v189, v176, v189
	v_add_f32_e32 v189, v179, v189
	v_mfma_f32_32x32x16_bf16 v[32:47], v[60:63], v[250:253], v[32:47]
	v_exp_f32_e32 v96, v96
	v_exp_f32_e32 v97, v97
	v_add_f32_e32 v189, v175, v189
	v_add_f32_e32 v189, v177, v189
	v_add_f32_e32 v189, v173, v189
	s_waitcnt lgkmcnt(4)
	v_mfma_f32_32x32x16_bf16 v[16:31], v[56:59], v[190:193], v[16:31]
	v_exp_f32_e32 v98, v98
	v_exp_f32_e32 v99, v99
	v_add_f32_e32 v189, v174, v189
	v_add_f32_e32 v189, v64, v189
	v_add_f32_e32 v189, v65, v189
	s_waitcnt lgkmcnt(1)
	v_mfma_f32_32x32x16_bf16 v[16:31], v[60:63], v[194:197], v[16:31]
	v_exp_f32_e32 v100, v100
	v_exp_f32_e32 v101, v101
	v_add_f32_e32 v189, v66, v189
	v_add_f32_e32 v189, v67, v189
	v_add_f32_e32 v189, v68, v189
	s_waitcnt vmcnt(2) lgkmcnt(0)
	s_barrier
; #define LAS __attribute__((address_space(3)))
; __device__ __forceinline__ void qkt(f32x16& p0, f32x16& p1, const char* Ks, const bf16x8* qr, const f32x16& negm, int r32, int hi) {
; #pragma unroll
;     for (int d0 = 0; d0 < 4; ++d0) { const int cb = (d0 * 16 + hi * 8) * 2;
;         const bf16x8 b0 = *reinterpret_cast<const bf16x8*>(Ks + KSWZ(r32, cb));
;         const bf16x8 b1 = *reinterpret_cast<const bf16x8*>(Ks + KSWZ(r32, 128 + cb));
;         if (d0 == 0) { p0 = __builtin_amdgcn_mfma_f32_32x32x16_bf16(b0, qr[0], negm, 0, 0, 0); p1 = __builtin_amdgcn_mfma_f32_32x32x16_bf16(b1, qr[0], negm, 0, 0, 0); }
;         else { p0 = __builtin_amdgcn_mfma_f32_32x32x16_bf16(b0, qr[d0], p0, 0, 0, 0); p1 = __builtin_amdgcn_mfma_f32_32x32x16_bf16(b1, qr[d0], p1, 0, 0, 0); } }
; }
; __device__ __forceinline__ int v_st(int k, int c) { const int kk = (k & ~0xC) | ((k & 4) << 1) | ((k & 8) >> 1); return ((kk >> 3) * 2 + (c >> 5)) * 512 + ((kk & 7) * 32 + (c & 31)) * 2; }
; __device__ __forceinline__ int v_rd_base(int lane) { return (((lane & 3) << 3) | (((lane >> 2) & 3) << 6) | (((lane >> 4) & 1) << 5)) + ((lane >> 5) & 1) * 1024; }
; template <int OFF> __device__ __forceinline__ s16x4 tr_read(int vb) {
;     return __builtin_bit_cast(s16x4, __builtin_amdgcn_ds_read_tr16_b64_v4i16((LAS v4i16_t*)(unsigned)(vb + OFF)));
; }
; template <int D0> __device__ __forceinline__ void pv_one(f32x16& od, int vb, bf16x8 pa0, bf16x8 pa1, bf16x8 pa2, bf16x8 pa3) {
;     const s16x4 l0 = tr_read<v_rd_off(D0, 0, 0)>(vb), h0 = tr_read<v_rd_off(D0, 0, 1)>(vb), l1 = tr_read<v_rd_off(D0, 1, 0)>(vb), h1 = tr_read<v_rd_off(D0, 1, 1)>(vb);
;     const s16x4 l2 = tr_read<v_rd_off(D0, 2, 0)>(vb), h2 = tr_read<v_rd_off(D0, 2, 1)>(vb), l3 = tr_read<v_rd_off(D0, 3, 0)>(vb), h3 = tr_read<v_rd_off(D0, 3, 1)>(vb);
;     ...
;     od = __builtin_amdgcn_mfma_f32_32x32x16_bf16(pa0, PK(l0, h0), od, 0, 0, 0);
;     od = __builtin_amdgcn_mfma_f32_32x32x16_bf16(pa1, PK(l1, h1), od, 0, 0, 0);
;     od = __builtin_amdgcn_mfma_f32_32x32x16_bf16(pa2, PK(l2, h2), od, 0, 0, 0);
;     od = __builtin_amdgcn_mfma_f32_32x32x16_bf16(pa3, PK(l3, h3), od, 0, 0, 0);
;     ...
; }
	v_mfma_f32_32x32x16_bf16 v[80:95], v[234:237], v[124:127], v[0:15]
	ds_read_b128 v[234:237], v163 offset:32768
	v_exp_f32_e32 v102, v102
	v_exp_f32_e32 v103, v103
	v_add_f32_e32 v189, v69, v189
	v_add_f32_e32 v189, v70, v189
	v_add_f32_e32 v189, v71, v189
	v_mfma_f32_32x32x16_bf16 v[80:95], v[238:241], v[120:123], v[80:95]
	ds_read_b128 v[238:241], v165 offset:32768
	v_exp_f32_e32 v104, v104
	v_exp_f32_e32 v105, v105
	v_exp_f32_e32 v106, v106
	v_add_f32_e32 v189, v72, v189
	v_add_f32_e32 v189, v73, v189
	v_mfma_f32_32x32x16_bf16 v[80:95], v[242:245], v[116:119], v[80:95]
	ds_read_b128 v[242:245], v167 offset:32768
	v_exp_f32_e32 v107, v107
	v_exp_f32_e32 v108, v108
	v_exp_f32_e32 v109, v109
	v_add_f32_e32 v189, v74, v189
	v_add_f32_e32 v189, v75, v189
	v_mfma_f32_32x32x16_bf16 v[80:95], v[246:249], v[112:115], v[80:95]
	ds_read_b128 v[246:249], v169 offset:32768
	v_exp_f32_e32 v110, v110
	v_exp_f32_e32 v111, v111
	v_add_f32_e32 v189, v76, v189
	v_add_f32_e32 v189, v77, v189
	v_add_f32_e32 v189, v78, v189
	v_add_f32_e32 v189, v79, v189
	v_add_f32_e32 v160, v160, v189
	s_add_i32 m0, s26, 0xc000
	s_nop 0
	global_load_lds_dwordx4 v[140:141], off
	s_add_i32 m0, s26, 0x4000
	v_lshl_add_u64 v[140:141], v[140:141], 0, s[62:63]
	global_load_lds_dwordx4 v[142:143], off
	v_lshl_add_u64 v[142:143], v[142:143], 0, s[62:63]
	s_waitcnt lgkmcnt(3)
	v_mfma_f32_32x32x16_bf16 v[218:233], v[234:237], v[124:127], v[0:15]
	ds_read_b64_tr_b16 v[190:191], v172 offset:24576
	ds_read_b64_tr_b16 v[192:193], v172 offset:24832
	v_add_f32_e32 v189, v96, v97
	v_add_f32_e32 v189, v98, v189
	v_add_f32_e32 v189, v99, v189
	v_add_f32_e32 v189, v100, v189
	v_exp_f32_e32 v80, v80
	s_waitcnt lgkmcnt(4)
	v_mfma_f32_32x32x16_bf16 v[218:233], v[238:241], v[120:123], v[218:233]
	ds_read_b64_tr_b16 v[194:195], v172 offset:26624
	ds_read_b64_tr_b16 v[196:197], v172 offset:26880
	v_exp_f32_e32 v81, v81
	v_cvt_pk_bf16_f32 v48, v96, v97
	v_exp_f32_e32 v82, v82
	v_exp_f32_e32 v83, v83
	s_waitcnt lgkmcnt(5)
	v_mfma_f32_32x32x16_bf16 v[218:233], v[242:245], v[116:119], v[218:233]
	ds_read_b64_tr_b16 v[144:145], v172 offset:28672
	ds_read_b64_tr_b16 v[146:147], v172 offset:28928
	v_cvt_pk_bf16_f32 v49, v98, v99
	v_exp_f32_e32 v84, v84
	v_exp_f32_e32 v85, v85
	v_cvt_pk_bf16_f32 v50, v100, v101
	s_waitcnt lgkmcnt(6)
	v_mfma_f32_32x32x16_bf16 v[218:233], v[246:249], v[112:115], v[218:233]
	ds_read_b64_tr_b16 v[250:251], v172 offset:30720
	ds_read_b64_tr_b16 v[252:253], v172 offset:30976
	v_exp_f32_e32 v86, v86
	v_exp_f32_e32 v87, v87
	v_cvt_pk_bf16_f32 v51, v102, v103
	v_cvt_pk_bf16_f32 v52, v104, v105
	s_waitcnt lgkmcnt(6)
	v_mfma_f32_32x32x16_bf16 v[32:47], v[48:51], v[190:193], v[32:47]
	ds_read_b64_tr_b16 v[190:191], v172 offset:25088
	ds_read_b64_tr_b16 v[192:193], v172 offset:25344
	ds_read_b128 v[234:237], v164 offset:32768
	v_cvt_pk_bf16_f32 v53, v106, v107
	v_cvt_pk_bf16_f32 v54, v108, v109
	v_cvt_pk_bf16_f32 v55, v110, v111
	v_cvt_pk_bf16_f32 v56, v80, v81
	v_cvt_pk_bf16_f32 v57, v82, v83
	v_exp_f32_e32 v88, v88
	s_waitcnt lgkmcnt(7)
	v_mfma_f32_32x32x16_bf16 v[32:47], v[52:55], v[194:197], v[32:47]
	ds_read_b64_tr_b16 v[194:195], v172 offset:27136
	ds_read_b64_tr_b16 v[196:197], v172 offset:27392
	ds_read_b128 v[238:241], v166 offset:32768
	v_cvt_pk_bf16_f32 v58, v84, v85
	v_cvt_pk_bf16_f32 v59, v86, v87
	v_exp_f32_e32 v89, v89
	v_exp_f32_e32 v90, v90
	s_waitcnt lgkmcnt(4)
	v_mfma_f32_32x32x16_bf16 v[16:31], v[48:51], v[190:193], v[16:31]
	ds_read_b64_tr_b16 v[190:191], v172 offset:29184
	ds_read_b64_tr_b16 v[192:193], v172 offset:29440
	ds_read_b128 v[242:245], v168 offset:32768
	v_exp_f32_e32 v91, v91
	v_exp_f32_e32 v92, v92
	v_exp_f32_e32 v93, v93
	v_add_f32_e32 v189, v101, v189
	s_waitcnt lgkmcnt(4)
	v_mfma_f32_32x32x16_bf16 v[16:31], v[52:55], v[194:197], v[16:31]
	ds_read_b64_tr_b16 v[194:195], v172 offset:31232
	ds_read_b64_tr_b16 v[196:197], v172 offset:31488
	ds_read_b128 v[246:249], v170 offset:32768
	v_exp_f32_e32 v94, v94
	v_exp_f32_e32 v95, v95
	v_add_f32_e32 v189, v102, v189
	v_add_f32_e32 v189, v103, v189
	v_cvt_pk_bf16_f32 v60, v88, v89
	v_mfma_f32_32x32x16_bf16 v[32:47], v[56:59], v[144:147], v[32:47]
	v_cvt_pk_bf16_f32 v61, v90, v91
	v_cvt_pk_bf16_f32 v62, v92, v93
	v_cvt_pk_bf16_f32 v63, v94, v95
	v_add_f32_e32 v189, v104, v189
	v_add_f32_e32 v189, v105, v189
	v_add_f32_e32 v189, v106, v189
	v_add_f32_e32 v189, v107, v189
	v_mfma_f32_32x32x16_bf16 v[32:47], v[60:63], v[250:253], v[32:47]
	v_exp_f32_e32 v183, v218
	v_exp_f32_e32 v188, v219
	v_add_f32_e32 v189, v108, v189
	v_add_f32_e32 v189, v109, v189
	v_add_f32_e32 v189, v110, v189
	s_waitcnt lgkmcnt(4)
	v_mfma_f32_32x32x16_bf16 v[16:31], v[56:59], v[190:193], v[16:31]
	v_exp_f32_e32 v185, v220
	v_exp_f32_e32 v187, v221
	v_add_f32_e32 v189, v111, v189
	v_add_f32_e32 v189, v80, v189
	v_add_f32_e32 v189, v81, v189
	s_waitcnt lgkmcnt(1)
	v_mfma_f32_32x32x16_bf16 v[16:31], v[60:63], v[194:197], v[16:31]
	v_exp_f32_e32 v184, v222
	v_exp_f32_e32 v186, v223
	v_add_f32_e32 v189, v82, v189
	v_add_f32_e32 v189, v83, v189
	v_add_f32_e32 v189, v84, v189
	s_waitcnt vmcnt(2) lgkmcnt(0)
	s_barrier
; #define SBAR() __builtin_amdgcn_sched_barrier(0)
; #define DMA(t) do { const int t_ = (t) < NT ? (t) : NT - 1; const long off_ = (long)t_ * (KVBLK * LDK); \
;         __builtin_amdgcn_global_load_lds((const unsigned*)(kptr + off_), (LAS unsigned*)(ldsK + SLOT(t)), 16, 0, 0); \
;         __builtin_amdgcn_global_load_lds((const unsigned*)(vptr + off_), (LAS unsigned*)(ldsV + SLOT(t)), 16, 0, 0); } while (0)
; #define HALF(PX0, PX1, PY0, PY1, j_, MORE) do { \
;         SBAR(); if (MORE) DMA((j_) + 2); qkt(PX0, PX1, K_lds + SLOT(j_), qr, negm, r32, hi); \
;         finishSM(PY0, PY1, l_reg, pa0, pa1, pa2, pa3); \
;         pv_d0(o, vb0 + SLOT((j_) - 1), pa0, pa1, pa2, pa3); partialSM(PX0); \
;         if (MORE) WBAR(2); else WBAR(0); } while (0)
; __device__ __forceinline__ void attn_body(const bf16* __restrict__ Qb, const bf16* __restrict__ Kh, const bf16* __restrict__ Vh, bf16* __restrict__ Ob, int seq, float m0l2, char* lds, bool pre, bool post) {
;     ...
;     for (; j + 4 < NT; j += 2) {
;         HALF(pB0, pB1, pA0, pA1, j, true);
;         HALF(pA0, pA1, pB0, pB1, j + 1, true);
;     }
;     HALF(pB0, pB1, pA0, pA1, j, true);
;     HALF(pA0, pA1, pB0, pB1, j + 1, false);
;     if (post) { DMA(0); DMA(1); }
;     SBAR(); qkt(pB0, pB1, K_lds + SLOT(NT - 1), qr, negm, r32, hi);
;     finishSM(pA0, pA1, l_reg, pa0, pa1, pa2, pa3); SBAR();
;     pv_d0(o, vb0 + SLOT(NT - 2), pa0, pa1, pa2, pa3); partialSM(pB0);
	v_mfma_f32_32x32x16_bf16 v[64:79], v[234:237], v[124:127], v[0:15]
	ds_read_b128 v[234:237], v163 offset:40960
	v_exp_f32_e32 v181, v224
	v_exp_f32_e32 v182, v225
	v_add_f32_e32 v189, v85, v189
	v_add_f32_e32 v189, v86, v189
	v_add_f32_e32 v189, v87, v189
	v_mfma_f32_32x32x16_bf16 v[64:79], v[238:241], v[120:123], v[64:79]
	ds_read_b128 v[238:241], v165 offset:40960
	v_exp_f32_e32 v178, v226
	v_exp_f32_e32 v180, v227
	v_exp_f32_e32 v176, v228
	v_add_f32_e32 v189, v88, v189
	v_add_f32_e32 v189, v89, v189
	v_mfma_f32_32x32x16_bf16 v[64:79], v[242:245], v[116:119], v[64:79]
	ds_read_b128 v[242:245], v167 offset:40960
	v_exp_f32_e32 v179, v229
	v_exp_f32_e32 v175, v230
	v_exp_f32_e32 v177, v231
	v_add_f32_e32 v189, v90, v189
	v_add_f32_e32 v189, v91, v189
	v_mfma_f32_32x32x16_bf16 v[64:79], v[246:249], v[112:115], v[64:79]
	ds_read_b128 v[246:249], v169 offset:40960
	v_exp_f32_e32 v173, v232
	v_exp_f32_e32 v174, v233
	v_add_f32_e32 v189, v92, v189
	v_add_f32_e32 v189, v93, v189
	v_add_f32_e32 v189, v94, v189
	v_add_f32_e32 v189, v95, v189
	v_add_f32_e32 v160, v160, v189
	s_add_i32 s7, s7, 4
	s_cmp_lt_u32 s7, 62
	s_cbranch_scc1 .LBB0_27
	s_waitcnt lgkmcnt(0)
	v_mov_b64_e32 v[48:49], v[0:1]
	v_mov_b64_e32 v[50:51], v[2:3]
	v_mov_b64_e32 v[52:53], v[4:5]
	v_mov_b64_e32 v[54:55], v[6:7]
	v_mov_b64_e32 v[56:57], v[8:9]
	v_mov_b64_e32 v[58:59], v[10:11]
	v_mov_b64_e32 v[60:61], v[12:13]
	v_mov_b64_e32 v[62:63], v[14:15]
	s_nop 7
	s_add_i32 s6, s6, s24
	s_cmpk_lt_i32 s6, 0x400
	s_cselect_b64 s[6:7], -1, 0
	s_or_b64 s[6:7], s[6:7], s[8:9]
	s_and_b64 s[6:7], s[86:87], s[6:7]
	s_mov_b64 s[38:39], 0x10c000
	v_lshl_add_u64 v[80:81], v[132:133], 0, s[38:39]
	s_add_i32 m0, s26, 0xe000
	v_add_u32_e32 v172, 0, v129
	global_load_lds_dwordx4 v[80:81], off
	v_lshl_add_u64 v[80:81], v[134:135], 0, s[38:39]
	s_add_i32 m0, s26, 0x6000
	s_cmp_lg_u32 0, -1
	global_load_lds_dwordx4 v[80:81], off
	ds_read_b128 v[96:99], v154 offset:40960
	ds_read_b128 v[140:143], v162 offset:40960
	s_waitcnt lgkmcnt(0)
	v_mfma_f32_32x32x16_bf16 v[80:95], v[96:99], v[124:127], v[48:63]
	s_cselect_b32 s27, 0, 0
	v_add_u32_e32 v221, s27, v129
	v_exp_f32_e32 v144, v68
	v_exp_f32_e32 v145, v69
	v_exp_f32_e32 v146, v70
	v_exp_f32_e32 v147, v71
	v_exp_f32_e32 v163, v72
	v_mfma_f32_32x32x16_bf16 v[96:111], v[140:143], v[124:127], v[48:63]
	ds_read_b128 v[140:143], v153 offset:40960
	v_exp_f32_e32 v168, v77
	v_exp_f32_e32 v169, v78
	v_exp_f32_e32 v170, v79
	s_waitcnt lgkmcnt(0)
	v_mfma_f32_32x32x16_bf16 v[80:95], v[140:143], v[120:123], v[80:95]
	ds_read_b128 v[140:143], v157 offset:40960
	s_waitcnt lgkmcnt(0)
	v_mfma_f32_32x32x16_bf16 v[96:111], v[140:143], v[120:123], v[96:111]
	ds_read_b128 v[140:143], v156 offset:40960
	s_waitcnt lgkmcnt(0)
	v_mfma_f32_32x32x16_bf16 v[80:95], v[140:143], v[116:119], v[80:95]
	ds_read_b128 v[140:143], v158 offset:40960
	ds_read_b128 v[164:167], v155 offset:40960
	ds_read_b128 v[190:193], v159 offset:40960
	s_waitcnt lgkmcnt(0)
	v_mfma_f32_32x32x16_bf16 v[96:111], v[140:143], v[116:119], v[96:111]
	v_exp_f32_e32 v140, v64
	v_exp_f32_e32 v141, v65
	v_exp_f32_e32 v142, v66
	v_exp_f32_e32 v143, v67
	v_cvt_pk_bf16_f32 v64, v183, v188
	v_cvt_pk_bf16_f32 v65, v185, v187
	v_cvt_pk_bf16_f32 v66, v184, v186
	v_mfma_f32_32x32x16_bf16 v[80:95], v[164:167], v[112:115], v[80:95]
	v_exp_f32_e32 v164, v73
	v_exp_f32_e32 v165, v74
	v_exp_f32_e32 v166, v75
	v_exp_f32_e32 v167, v76
	v_cvt_pk_bf16_f32 v67, v181, v182
	v_cvt_pk_bf16_f32 v68, v178, v180
	v_cvt_pk_bf16_f32 v69, v176, v179
	v_mfma_f32_32x32x16_bf16 v[96:111], v[190:193], v[112:115], v[96:111]
	v_cvt_pk_bf16_f32 v70, v175, v177
	v_cvt_pk_bf16_f32 v71, v173, v174
	v_cvt_pk_bf16_f32 v72, v140, v141
	v_cvt_pk_bf16_f32 v73, v142, v143
	v_cvt_pk_bf16_f32 v74, v144, v145
	v_cvt_pk_bf16_f32 v75, v146, v147
	v_cvt_pk_bf16_f32 v76, v163, v164
	v_cvt_pk_bf16_f32 v77, v165, v166
	v_cvt_pk_bf16_f32 v78, v167, v168
	v_cvt_pk_bf16_f32 v79, v169, v170
	ds_read_b64_tr_b16 v[190:191], v172
	ds_read_b64_tr_b16 v[192:193], v221 offset:256
	s_waitcnt lgkmcnt(0)
	v_mfma_f32_32x32x16_bf16 v[32:47], v[64:67], v[190:193], v[32:47]
	ds_read_b64_tr_b16 v[190:191], v221 offset:2048
	ds_read_b64_tr_b16 v[192:193], v221 offset:2304
	s_nop 0
	v_exp_f32_e32 v172, v80
	v_exp_f32_e32 v189, v81
	v_exp_f32_e32 v198, v90
	v_exp_f32_e32 v199, v91
	v_exp_f32_e32 v217, v92
	v_exp_f32_e32 v218, v93
	s_waitcnt lgkmcnt(0)
	v_mfma_f32_32x32x16_bf16 v[32:47], v[68:71], v[190:193], v[32:47]
	ds_read_b64_tr_b16 v[190:191], v221 offset:4096
	ds_read_b64_tr_b16 v[192:193], v221 offset:4352
	v_exp_f32_e32 v219, v94
	v_exp_f32_e32 v220, v95
	s_waitcnt lgkmcnt(0)
	v_mfma_f32_32x32x16_bf16 v[32:47], v[72:75], v[190:193], v[32:47]
	ds_read_b64_tr_b16 v[190:191], v221 offset:6144
	ds_read_b64_tr_b16 v[192:193], v221 offset:6400
	s_waitcnt lgkmcnt(0)
	v_mfma_f32_32x32x16_bf16 v[32:47], v[76:79], v[190:193], v[32:47]
	ds_read_b64_tr_b16 v[190:191], v221 offset:512
	ds_read_b64_tr_b16 v[192:193], v221 offset:768
	ds_read_b64_tr_b16 v[194:195], v221 offset:2560
	s_waitcnt lgkmcnt(0)
	v_mfma_f32_32x32x16_bf16 v[16:31], v[64:67], v[190:193], v[16:31]
	ds_read_b64_tr_b16 v[196:197], v221 offset:2816
	ds_read_b64_tr_b16 v[64:65], v221 offset:4608
	ds_read_b64_tr_b16 v[66:67], v221 offset:4864
	ds_read_b64_tr_b16 v[222:223], v221 offset:6656
	ds_read_b64_tr_b16 v[224:225], v221 offset:6912
	v_exp_f32_e32 v190, v82
	v_exp_f32_e32 v191, v83
	v_exp_f32_e32 v192, v84
	v_exp_f32_e32 v193, v85
	s_waitcnt vmcnt(2) lgkmcnt(0)
	s_barrier
; #define SBAR() __builtin_amdgcn_sched_barrier(0)
; #define DMA(t) do { const int t_ = (t) < NT ? (t) : NT - 1; const long off_ = (long)t_ * (KVBLK * LDK); \
;         __builtin_amdgcn_global_load_lds((const unsigned*)(kptr + off_), (LAS unsigned*)(ldsK + SLOT(t)), 16, 0, 0); \
;         __builtin_amdgcn_global_load_lds((const unsigned*)(vptr + off_), (LAS unsigned*)(ldsV + SLOT(t)), 16, 0, 0); } while (0)
; #define HALF(PX0, PX1, PY0, PY1, j_, MORE) do { \
;         SBAR(); if (MORE) DMA((j_) + 2); qkt(PX0, PX1, K_lds + SLOT(j_), qr, negm, r32, hi); \
;         finishSM(PY0, PY1, l_reg, pa0, pa1, pa2, pa3); \
;         pv_d0(o, vb0 + SLOT((j_) - 1), pa0, pa1, pa2, pa3); partialSM(PX0); \
;         if (MORE) WBAR(2); else WBAR(0); } while (0)
; __device__ __forceinline__ void attn_body(const bf16* __restrict__ Qb, const bf16* __restrict__ Kh, const bf16* __restrict__ Vh, bf16* __restrict__ Ob, int seq, float m0l2, char* lds, bool pre, bool post) {
;     ...
;     HALF(pB0, pB1, pA0, pA1, j, true);
;     HALF(pA0, pA1, pB0, pB1, j + 1, false);
;     if (post) { DMA(0); DMA(1); }
;     SBAR(); qkt(pB0, pB1, K_lds + SLOT(NT - 1), qr, negm, r32, hi);
	s_waitcnt lgkmcnt(0)
	v_mfma_f32_32x32x16_bf16 v[16:31], v[68:71], v[194:197], v[16:31]
	v_exp_f32_e32 v194, v86
	v_exp_f32_e32 v195, v87
	v_exp_f32_e32 v196, v88
	v_exp_f32_e32 v197, v89
	v_mfma_f32_32x32x16_bf16 v[16:31], v[72:75], v[64:67], v[16:31]
	v_mfma_f32_32x32x16_bf16 v[16:31], v[76:79], v[222:225], v[16:31]
	ds_read_b128 v[64:67], v154 offset:49152
	ds_read_b128 v[222:225], v162 offset:49152
	v_exp_f32_e32 v96, v96
	v_exp_f32_e32 v97, v97
	v_exp_f32_e32 v98, v98
	v_exp_f32_e32 v99, v99
	v_exp_f32_e32 v100, v100
	v_exp_f32_e32 v101, v101
	v_exp_f32_e32 v102, v102
	s_waitcnt lgkmcnt(0)
	v_mfma_f32_32x32x16_bf16 v[80:95], v[64:67], v[124:127], v[48:63]
	v_exp_f32_e32 v103, v103
	v_exp_f32_e32 v104, v104
	v_exp_f32_e32 v105, v105
	v_exp_f32_e32 v106, v106
	v_exp_f32_e32 v107, v107
	v_exp_f32_e32 v108, v108
	v_exp_f32_e32 v109, v109
	v_mfma_f32_32x32x16_bf16 v[64:79], v[222:225], v[124:127], v[48:63]
	ds_read_b128 v[222:225], v153 offset:49152
	v_exp_f32_e32 v110, v110
	v_exp_f32_e32 v111, v111
	s_andn2_b64 vcc, exec, s[6:7]
	s_waitcnt lgkmcnt(0)
	v_mfma_f32_32x32x16_bf16 v[80:95], v[222:225], v[120:123], v[80:95]
	ds_read_b128 v[222:225], v157 offset:49152
	s_waitcnt lgkmcnt(0)
	v_mfma_f32_32x32x16_bf16 v[64:79], v[222:225], v[120:123], v[64:79]
	ds_read_b128 v[222:225], v156 offset:49152
	s_waitcnt lgkmcnt(0)
	v_mfma_f32_32x32x16_bf16 v[80:95], v[222:225], v[116:119], v[80:95]
	ds_read_b128 v[222:225], v158 offset:49152
	s_waitcnt lgkmcnt(0)
	v_mfma_f32_32x32x16_bf16 v[64:79], v[222:225], v[116:119], v[64:79]
	ds_read_b128 v[222:225], v155 offset:49152
	s_waitcnt lgkmcnt(0)
	v_mfma_f32_32x32x16_bf16 v[80:95], v[222:225], v[112:115], v[80:95]
	ds_read_b128 v[222:225], v159 offset:49152
	s_waitcnt lgkmcnt(0)
	v_mfma_f32_32x32x16_bf16 v[64:79], v[222:225], v[112:115], v[64:79]
	v_cvt_pk_bf16_f32 v222, v172, v189
	v_cvt_pk_bf16_f32 v223, v190, v191
	v_cvt_pk_bf16_f32 v224, v192, v193
	v_cvt_pk_bf16_f32 v225, v194, v195
	v_cvt_pk_bf16_f32 v226, v196, v197
	v_cvt_pk_bf16_f32 v227, v198, v199
	v_cvt_pk_bf16_f32 v228, v217, v218
	v_cvt_pk_bf16_f32 v229, v219, v220
	v_cvt_pk_bf16_f32 v230, v96, v97
	v_cvt_pk_bf16_f32 v231, v98, v99
	v_cvt_pk_bf16_f32 v232, v100, v101
	v_cvt_pk_bf16_f32 v233, v102, v103
	v_cvt_pk_bf16_f32 v234, v104, v105
	v_cvt_pk_bf16_f32 v235, v106, v107
	v_cvt_pk_bf16_f32 v236, v108, v109
	v_cvt_pk_bf16_f32 v237, v110, v111
	ds_read_b64_tr_b16 v[238:239], v221 offset:8192
	ds_read_b64_tr_b16 v[240:241], v221 offset:8448
	s_waitcnt lgkmcnt(0)
	v_mfma_f32_32x32x16_bf16 v[32:47], v[222:225], v[238:241], v[32:47]
	ds_read_b64_tr_b16 v[238:239], v221 offset:10240
	ds_read_b64_tr_b16 v[240:241], v221 offset:10496
	s_waitcnt lgkmcnt(0)
	v_mfma_f32_32x32x16_bf16 v[32:47], v[226:229], v[238:241], v[32:47]
	ds_read_b64_tr_b16 v[238:239], v221 offset:12288
	ds_read_b64_tr_b16 v[240:241], v221 offset:12544
	s_waitcnt lgkmcnt(0)
	v_mfma_f32_32x32x16_bf16 v[32:47], v[230:233], v[238:241], v[32:47]
	ds_read_b64_tr_b16 v[238:239], v221 offset:14336
	ds_read_b64_tr_b16 v[240:241], v221 offset:14592
	s_waitcnt lgkmcnt(0)
	v_mfma_f32_32x32x16_bf16 v[32:47], v[234:237], v[238:241], v[32:47]
	ds_read_b64_tr_b16 v[238:239], v221 offset:8704
	ds_read_b64_tr_b16 v[240:241], v221 offset:8960
	s_waitcnt lgkmcnt(0)
	v_mfma_f32_32x32x16_bf16 v[16:31], v[222:225], v[238:241], v[16:31]
	ds_read_b64_tr_b16 v[222:223], v221 offset:10752
	ds_read_b64_tr_b16 v[224:225], v221 offset:11008
	s_waitcnt lgkmcnt(0)
	v_mfma_f32_32x32x16_bf16 v[16:31], v[226:229], v[222:225], v[16:31]
	ds_read_b64_tr_b16 v[222:223], v221 offset:12800
	ds_read_b64_tr_b16 v[224:225], v221 offset:13056
	s_waitcnt lgkmcnt(0)
	v_mfma_f32_32x32x16_bf16 v[16:31], v[230:233], v[222:225], v[16:31]
	ds_read_b64_tr_b16 v[222:223], v221 offset:14848
	ds_read_b64_tr_b16 v[224:225], v221 offset:15104
	s_waitcnt vmcnt(0) lgkmcnt(0)
	s_barrier
	s_waitcnt lgkmcnt(0)
	v_mfma_f32_32x32x16_bf16 v[16:31], v[234:237], v[222:225], v[16:31]
	s_cbranch_vccnz .LBB0_30
	s_add_i32 m0, s26, 0x8000
	s_add_i32 s6, s26, 0xa000
	global_load_lds_dwordx4 v[132:133], off
	s_mov_b32 m0, s26
	s_add_i32 s7, s26, 0x2000
	global_load_lds_dwordx4 v[134:135], off
	s_mov_b32 m0, s6
	s_nop 0
	global_load_lds_dwordx4 v[136:137], off
	s_mov_b32 m0, s7
	s_nop 0
	global_load_lds_dwordx4 v[138:139], off

; __device__ __forceinline__ int tid_fresh() { int t = threadIdx.x; asm volatile("" : "+v"(t)); return t; }
; #define LAS __attribute__((address_space(3)))
; #define WBAR(N) asm volatile("s_waitcnt vmcnt(" #N ") lgkmcnt(0)\n\ts_barrier" ::: "memory")
; __device__ __forceinline__ void attn_body(const bf16* __restrict__ Qb, const bf16* __restrict__ Kh, const bf16* __restrict__ Vh, bf16* __restrict__ Ob, int seq, float m0l2, char* lds, bool pre, bool post) {
;     const int tid = tid_fresh(), wid = tid >> 6, lane = tid & 63, r32 = lane & 31, hi = lane >> 5;
;     char* V_lds = lds + OFF_V; char* K_lds = lds + OFF_K;
;     float* li_l = (float*)(lds + OFF_WS) + wid * 64;
;     float l_reg = 0; f32x16 o[2] = {}; bf16x8 qr[4];
;     f32x16 negm;
; #pragma unroll
;     for (int r = 0; r < 16; ++r) negm[r] = -m0l2;
;     asm volatile("" : "+v"(negm));
;     const bf16* Qw = Qb + (long)(wid * QBLK + r32) * LDQ + hi * 8;
; #pragma unroll
;     for (int d0 = 0; d0 < 4; ++d0) qr[d0] = __builtin_nontemporal_load(reinterpret_cast<const bf16x8*>(Qw + d0 * 16));
;     const int wsg = __builtin_amdgcn_readfirstlane(wid);
;     const int oo = (wsg * 64 + lane) * 16;
;     const int ksr = oo >> 8, kcolB = (oo & 255) ^ ((ksr & 15) << 4);
;     const bf16* kptr = Kh + (long)(ksr + 32 * (kcolB >> 7)) * LDK + ((kcolB & 127) >> 1);
;     const int vkk = ((oo >> 9) >> 1) * 8 + ((oo & 511) >> 6), vcc = ((oo >> 9) & 1) * 32 + ((oo & 63) >> 1);
;     const bf16* vptr = Vh + (long)((vkk & ~0xC) | ((vkk & 4) << 1) | ((vkk & 8) >> 1)) * LDK + vcc;
;     LAS unsigned char* const ldsK = (LAS unsigned char*)lds + OFF_K + wsg * 1024; LAS unsigned char* const ldsV = (LAS unsigned char*)lds + OFF_V + wsg * 1024;
;     const int vb0 = (int)(uintptr_t)V_lds + v_rd_base(lane);
;     const int NT = seq / KVBLK;
;     ...
;     f32x16 pA0, pA1, pB0, pB1; bf16x8 pa0, pa1, pa2, pa3;
;     ...
;     if (!pre) { DMA(0); DMA(1); } DMA(2); WBAR(2);
;     qkt(pA0, pA1, K_lds, qr, negm, r32, hi); partialSM(pA0);
; __global__ void __launch_bounds__(NTHR, 2) fwd_kernel(Args A_) {
;     ...
;                 if (hasctx) {
;                     const int b = bx & 7, h = bx >> 3; const size_t r0 = (size_t)b * RPB;
;                     att::attn_body(Qb + r0 * 512 + h * 64, Kb + r0 * 128 + (h >> 2) * 64, Vb + r0 * 128 + (h >> 2) * 64, MIXb + r0 * 1024 + h * 64, CTXL, m0l2, (char*)lds, chain, false);
.LBB0_32:
	s_andn2_b64 vcc, exec, s[8:9]
	s_cbranch_vccnz .LBB0_38
	v_mov_b32_e32 v114, v171
	v_readlane_b32 s6, v254, 6
	s_add_u32 s6, s14, s6
	v_ashrrev_i32_e32 v117, 6, v114
	v_and_b32_e32 v116, 31, v114
	v_lshlrev_b32_e32 v112, 5, v117
	s_addc_u32 s7, s15, 0
	v_readlane_b32 s8, v254, 61
	v_or_b32_e32 v16, v112, v116
	v_readlane_b32 s9, v254, 62
	s_add_u32 s6, s6, s8
	v_ashrrev_i32_e32 v17, 31, v16
	s_addc_u32 s7, s7, s9
	v_bfe_u32 v118, v114, 5, 1
	v_lshlrev_b64 v[16:17], 10, v[16:17]
	v_lshl_add_u64 v[16:17], s[6:7], 0, v[16:17]
	v_lshlrev_b32_e32 v160, 4, v118
	v_mov_b32_e32 v1, v0
	v_mov_b32_e32 v2, v0
	v_mov_b32_e32 v3, v0
	v_mov_b32_e32 v4, v0
	v_mov_b32_e32 v5, v0
	v_mov_b32_e32 v6, v0
	v_mov_b32_e32 v7, v0
	v_mov_b32_e32 v8, v0
	v_mov_b32_e32 v9, v0
	v_mov_b32_e32 v10, v0
	v_mov_b32_e32 v11, v0
	v_mov_b32_e32 v12, v0
	v_mov_b32_e32 v13, v0
	v_mov_b32_e32 v14, v0
	v_mov_b32_e32 v15, v0
	v_lshl_add_u64 v[16:17], v[16:17], 0, v[160:161]
	global_load_dwordx4 v[108:111], v[16:17], off nt
	global_load_dwordx4 v[104:107], v[16:17], off offset:32 nt
	global_load_dwordx4 v[100:103], v[16:17], off offset:64 nt
	global_load_dwordx4 v[96:99], v[16:17], off offset:96 nt
	v_readlane_b32 s8, v254, 58
	s_add_u32 s6, s19, s8
	s_addc_u32 s7, s22, 0
	v_readlane_b32 s10, v254, 59
	v_readlane_b32 s11, v254, 60
	s_add_u32 s6, s6, s10
	s_addc_u32 s7, s7, s11
	s_add_u32 s3, s3, s8
	s_addc_u32 s9, s13, 0
	s_add_u32 s8, s3, s10
	v_and_b32_e32 v115, 63, v114
	v_readfirstlane_b32 s3, v117
	s_addc_u32 s9, s9, s11
	s_lshl_b32 s3, s3, 10
	v_lshlrev_b32_e32 v16, 4, v115
	v_mov_b32_e32 v17, s3
	v_lshrrev_b32_e32 v20, 4, v17
	v_and_b32_e32 v20, 64, v20
	v_and_or_b32 v20, v115, 48, v20
	v_lshrrev_b32_e32 v17, 11, v17
	v_and_b32_e32 v18, 15, v115
	v_lshl_or_b32 v18, v17, 4, v18
	v_ashrrev_i32_e32 v19, 31, v18
	v_lshlrev_b64 v[18:19], 8, v[18:19]
	v_lshl_add_u64 v[18:19], s[6:7], 0, v[18:19]
	s_nop 0
	v_mov_b32_e32 v21, v161
	v_lshl_add_u64 v[48:49], v[18:19], 0, v[20:21]
	s_ashr_i32 s6, s3, 7
	v_lshrrev_b32_e32 v19, 1, v114
	v_bfe_u32 v18, v114, 2, 2
	s_and_b32 s7, s6, -16
	v_and_b32_e32 v19, 8, v19
	s_lshr_b32 s6, s6, 1
	v_or3_b32 v18, v19, v18, s7
	v_lshlrev_b32_e32 v17, 3, v114
	v_and_or_b32 v18, s6, 4, v18
	v_and_b32_e32 v17, 24, v17
	v_ashrrev_i32_e32 v19, 31, v18
	v_and_or_b32 v20, v114, 32, v17
	v_lshlrev_b64 v[18:19], 8, v[18:19]
	v_readlane_b32 s6, v254, 14
	v_lshl_add_u64 v[18:19], s[8:9], 0, v[18:19]
	v_lshlrev_b32_e32 v20, 1, v20
	v_readlane_b32 s7, v254, 15
	s_andn2_b64 vcc, exec, s[6:7]
	v_lshl_add_u64 v[50:51], v[18:19], 0, v[20:21]
	s_cbranch_vccnz .LBB0_35
	s_add_i32 s6, s3, 0
	s_add_i32 m0, s6, 0x8000
	s_mov_b64 s[8:9], 0x4000
	global_load_lds_dwordx4 v[48:49], off
	s_mov_b32 m0, s6
	v_lshl_add_u64 v[18:19], v[48:49], 0, s[8:9]
	global_load_lds_dwordx4 v[50:51], off
	s_add_i32 m0, s6, 0xa000
	v_lshl_add_u64 v[20:21], v[50:51], 0, s[8:9]
	global_load_lds_dwordx4 v[18:19], off
	s_add_i32 m0, s6, 0x2000
	s_nop 0
	global_load_lds_dwordx4 v[20:21], off
.LBB0_35:
	v_and_b32_e32 v18, 0x3fffffc0, v114
	s_add_i32 s6, 0, 0x10000
	v_lshl_add_u32 v113, v18, 2, s6
	v_lshlrev_b32_e32 v18, 1, v115
	v_and_b32_e32 v18, 32, v18
	s_movk_i32 s6, 0xc0
	v_and_or_b32 v16, v16, s6, v18
	v_lshlrev_b32_e32 v18, 5, v115
	v_and_b32_e32 v18, 0x400, v18
	s_add_i32 s3, s3, 0
	v_or3_b32 v119, v16, v18, v17
	v_lshl_add_u64 v[16:17], v[48:49], 0, s[82:83]
	s_add_i32 m0, s3, 0xc000
	v_lshlrev_b32_e32 v60, 8, v116
	global_load_lds_dwordx4 v[16:17], off
	v_lshl_add_u64 v[16:17], v[50:51], 0, s[82:83]
	s_add_i32 m0, s3, 0x4000
	v_or_b32_e32 v56, 32, v160
	global_load_lds_dwordx4 v[16:17], off
	v_lshlrev_b32_e32 v16, 4, v116
	v_and_b32_e32 v61, 0xf0, v16
	v_lshrrev_b32_e32 v60, 4, v116
	v_lshlrev_b32_e32 v60, 11, v60
	v_lshl_add_u32 v60, v160, 4, v60
	v_add_u32_e32 v60, v60, v61
	v_or_b32_e32 v16, 0x80, v160
	v_add_u32_e32 v16, 4096, v60
	v_add_u32_e32 v120, 0, v16
	v_mov_b32_e32 v16, v60
	s_waitcnt vmcnt(2) lgkmcnt(0)
	s_barrier
	v_add_u32_e32 v121, 0, v16
	ds_read_b128 v[52:55], v120 offset:32768
	ds_read_b128 v[16:19], v121 offset:32768
	s_waitcnt vmcnt(0) lgkmcnt(0)
	v_mfma_f32_32x32x16_bf16 v[32:47], v[16:19], v[108:111], v[0:15]
	v_add_u32_e32 v56, 512, v60
	v_add_u32_e32 v123, 0, v56
	ds_read_b128 v[56:59], v123 offset:32768
	v_mfma_f32_32x32x16_bf16 v[16:31], v[52:55], v[108:111], v[0:15]
	v_or_b32_e32 v52, 0xa0, v160
	v_add_u32_e32 v52, 4608, v60
	v_add_u32_e32 v122, 0, v52
	ds_read_b128 v[52:55], v122 offset:32768
	s_waitcnt lgkmcnt(1)
	v_mfma_f32_32x32x16_bf16 v[32:47], v[56:59], v[104:107], v[32:47]
	v_or_b32_e32 v56, 64, v160
	v_add_u32_e32 v56, 1024, v60
	v_add_u32_e32 v125, 0, v56
	ds_read_b128 v[56:59], v125 offset:32768
	s_waitcnt lgkmcnt(1)
	v_mfma_f32_32x32x16_bf16 v[16:31], v[52:55], v[104:107], v[16:31]
	v_or_b32_e32 v52, 0xc0, v160
	v_add_u32_e32 v52, 5120, v60
	v_add_u32_e32 v124, 0, v52
	ds_read_b128 v[52:55], v124 offset:32768
	s_waitcnt lgkmcnt(1)
	v_mfma_f32_32x32x16_bf16 v[32:47], v[56:59], v[100:103], v[32:47]
	v_or_b32_e32 v56, 0x60, v160
	v_add_u32_e32 v56, 1536, v60
	v_add_u32_e32 v127, 0, v56
	ds_read_b128 v[56:59], v127 offset:32768
	s_waitcnt lgkmcnt(1)
	v_mfma_f32_32x32x16_bf16 v[16:31], v[52:55], v[100:103], v[16:31]
	v_or_b32_e32 v52, 0xe0, v160
	v_add_u32_e32 v52, 5632, v60
	v_add_u32_e32 v126, 0, v52
	ds_read_b128 v[52:55], v126 offset:32768
	s_waitcnt lgkmcnt(1)
	v_mfma_f32_32x32x16_bf16 v[32:47], v[56:59], v[96:99], v[32:47]
	s_waitcnt lgkmcnt(0)
; #define DMA(t) do { const int t_ = (t) < NT ? (t) : NT - 1; const long off_ = (long)t_ * (KVBLK * LDK); \
;         __builtin_amdgcn_global_load_lds((const unsigned*)(kptr + off_), (LAS unsigned*)(ldsK + SLOT(t)), 16, 0, 0); \
;         __builtin_amdgcn_global_load_lds((const unsigned*)(vptr + off_), (LAS unsigned*)(ldsV + SLOT(t)), 16, 0, 0); } while (0)
; #define WBAR(N) asm volatile("s_waitcnt vmcnt(" #N ") lgkmcnt(0)\n\ts_barrier" ::: "memory")
; #define HALF(PX0, PX1, PY0, PY1, j_, MORE) do { \
;         SBAR(); if (MORE) DMA((j_) + 2); qkt(PX0, PX1, K_lds + SLOT(j_), qr, negm, r32, hi); \
;         finishSM(PY0, PY1, l_reg, pa0, pa1, pa2, pa3); \
;         pv_d0(o, vb0 + SLOT((j_) - 1), pa0, pa1, pa2, pa3); partialSM(PX0); \
;         if (MORE) WBAR(2); else WBAR(0); } while (0)
; __device__ __forceinline__ void attn_body(const bf16* __restrict__ Qb, const bf16* __restrict__ Kh, const bf16* __restrict__ Vh, bf16* __restrict__ Ob, int seq, float m0l2, char* lds, bool pre, bool post) {
;     ...
;     if (!pre) { DMA(0); DMA(1); } DMA(2); WBAR(2);
;     qkt(pA0, pA1, K_lds, qr, negm, r32, hi); partialSM(pA0);
;     int j = 1;
;     for (; j + 4 < NT; j += 2) {
;         HALF(pB0, pB1, pA0, pA1, j, true);
;         HALF(pA0, pA1, pB0, pB1, j + 1, true);
;     }
;     HALF(pB0, pB1, pA0, pA1, j, true);
	v_mfma_f32_32x32x16_bf16 v[16:31], v[52:55], v[96:99], v[16:31]
	s_nop 9
	v_exp_f32_e32 v80, v32
	v_exp_f32_e32 v81, v33
	v_exp_f32_e32 v82, v34
	v_exp_f32_e32 v83, v35
	v_exp_f32_e32 v92, v36
	v_exp_f32_e32 v128, v37
	v_exp_f32_e32 v129, v38
	v_exp_f32_e32 v130, v39
	v_exp_f32_e32 v131, v40
	v_exp_f32_e32 v132, v41
	v_exp_f32_e32 v133, v42
	v_exp_f32_e32 v134, v43
	v_exp_f32_e32 v135, v44
	v_exp_f32_e32 v136, v45
	v_exp_f32_e32 v137, v46
	v_exp_f32_e32 v138, v47
	s_mov_b64 s[6:7], 0xc000
	v_lshl_add_u64 v[32:33], v[48:49], 0, s[6:7]
	s_add_i32 m0, s3, 0xe000
	v_exp_f32_e32 v139, v16
	global_load_lds_dwordx4 v[32:33], off
	v_lshl_add_u64 v[32:33], v[50:51], 0, s[6:7]
	s_add_i32 m0, s3, 0x6000
	v_add_f32_e32 v16, v80, v81
	global_load_lds_dwordx4 v[32:33], off
	ds_read_b128 v[32:35], v121 offset:40960
	v_add_f32_e32 v16, v82, v16
	s_waitcnt lgkmcnt(0)
	v_mfma_f32_32x32x16_bf16 v[48:63], v[32:35], v[108:111], v[0:15]
	ds_read_b128 v[32:35], v120 offset:40960
	ds_read_b128 v[36:39], v122 offset:40960
	ds_read_b128 v[40:43], v123 offset:40960
	ds_read_b128 v[44:47], v124 offset:40960
	s_cmp_lg_u32 0, -1
	v_add_f32_e32 v16, v83, v16
	s_cselect_b32 s3, 0, 0
	v_exp_f32_e32 v140, v17
	v_exp_f32_e32 v141, v18
	v_exp_f32_e32 v142, v19
	s_waitcnt lgkmcnt(0)
	v_mfma_f32_32x32x16_bf16 v[48:63], v[40:43], v[104:107], v[48:63]
	v_exp_f32_e32 v40, v20
	v_add_f32_e32 v20, v92, v16
	v_add_u32_e32 v16, 0, v119
	v_add_u32_e32 v119, s3, v119
	v_exp_f32_e32 v41, v21
	v_exp_f32_e32 v42, v22
	v_exp_f32_e32 v43, v23
	v_mfma_f32_32x32x16_bf16 v[64:79], v[32:35], v[108:111], v[0:15]
	ds_read_b128 v[32:35], v125 offset:40960
	ds_read_b128 v[88:91], v126 offset:40960
	ds_read_b128 v[84:87], v127 offset:40960
	v_exp_f32_e32 v143, v24
	v_exp_f32_e32 v144, v25
	v_exp_f32_e32 v145, v26
	v_exp_f32_e32 v146, v27
	v_exp_f32_e32 v147, v28
	v_exp_f32_e32 v149, v29
	s_waitcnt lgkmcnt(0)
	v_mfma_f32_32x32x16_bf16 v[48:63], v[32:35], v[100:103], v[48:63]
	v_exp_f32_e32 v150, v30
	v_exp_f32_e32 v151, v31
	v_cvt_pk_bf16_f32 v32, v80, v81
	v_cvt_pk_bf16_f32 v33, v82, v83
	v_cvt_pk_bf16_f32 v34, v92, v128
	v_cvt_pk_bf16_f32 v35, v129, v130
	v_cvt_pk_bf16_f32 v92, v131, v132
	v_mfma_f32_32x32x16_bf16 v[64:79], v[36:39], v[104:107], v[64:79]
	v_cvt_pk_bf16_f32 v93, v133, v134
	v_cvt_pk_bf16_f32 v94, v135, v136
	v_cvt_pk_bf16_f32 v95, v137, v138
	v_cvt_pk_bf16_f32 v80, v139, v140
	v_cvt_pk_bf16_f32 v81, v141, v142
	v_cvt_pk_bf16_f32 v82, v40, v41
	v_cvt_pk_bf16_f32 v83, v42, v43
	v_mfma_f32_32x32x16_bf16 v[48:63], v[84:87], v[96:99], v[48:63]
	v_cvt_pk_bf16_f32 v84, v143, v144
	v_cvt_pk_bf16_f32 v85, v145, v146
	v_cvt_pk_bf16_f32 v86, v147, v149
	v_cvt_pk_bf16_f32 v87, v150, v151
	ds_read_b64_tr_b16 v[16:17], v16
	ds_read_b64_tr_b16 v[18:19], v119 offset:256
	v_add_f32_e32 v20, v128, v20
	v_add_f32_e32 v20, v129, v20
	v_add_f32_e32 v20, v130, v20
	v_add_f32_e32 v36, v131, v20
	s_waitcnt lgkmcnt(0)
	v_mfma_f32_32x32x16_bf16 v[16:31], v[32:35], v[16:19], 0
	s_nop 3
	v_exp_f32_e32 v152, v62
	v_exp_f32_e32 v153, v63
	v_mfma_f32_32x32x16_bf16 v[64:79], v[44:47], v[100:103], v[64:79]
	v_add_f32_e32 v44, v132, v36
	ds_read_b64_tr_b16 v[36:37], v119 offset:2048
	ds_read_b64_tr_b16 v[38:39], v119 offset:2304
	v_add_f32_e32 v44, v133, v44
	v_add_f32_e32 v44, v134, v44
	v_add_f32_e32 v44, v135, v44
	v_add_f32_e32 v44, v136, v44
	v_add_f32_e32 v44, v137, v44
	s_waitcnt lgkmcnt(0)
	v_mfma_f32_32x32x16_bf16 v[16:31], v[92:95], v[36:39], v[16:31]
	ds_read_b64_tr_b16 v[36:37], v119 offset:4096
	ds_read_b64_tr_b16 v[38:39], v119 offset:4352
	v_add_f32_e32 v44, v138, v44
	v_add_f32_e32 v44, v139, v44
	v_add_f32_e32 v44, v140, v44
	v_add_f32_e32 v44, v141, v44
	v_add_f32_e32 v44, v142, v44
	v_add_f32_e32 v40, v40, v44
	s_waitcnt lgkmcnt(0)
	v_mfma_f32_32x32x16_bf16 v[16:31], v[80:83], v[36:39], v[16:31]
	ds_read_b64_tr_b16 v[36:37], v119 offset:6144
	ds_read_b64_tr_b16 v[38:39], v119 offset:6400
	v_add_f32_e32 v40, v41, v40
	v_add_f32_e32 v40, v42, v40
	v_add_f32_e32 v40, v43, v40
	v_add_f32_e32 v40, v143, v40
	v_add_f32_e32 v40, v144, v40
	v_add_f32_e32 v40, v145, v40
	s_waitcnt lgkmcnt(0)
	v_mfma_f32_32x32x16_bf16 v[16:31], v[84:87], v[36:39], v[16:31]
	ds_read_b64_tr_b16 v[36:37], v119 offset:512
	ds_read_b64_tr_b16 v[38:39], v119 offset:768
	v_add_f32_e32 v40, v146, v40
	v_exp_f32_e32 v137, v48
	v_exp_f32_e32 v138, v49
	v_exp_f32_e32 v139, v50
	v_exp_f32_e32 v140, v51
	v_exp_f32_e32 v141, v52
	v_mfma_f32_32x32x16_bf16 v[64:79], v[88:91], v[96:99], v[64:79]
	v_add_f32_e32 v88, v147, v40
	v_add_f32_e32 v128, v149, v88
	ds_read_b64_tr_b16 v[88:89], v119 offset:2560
	ds_read_b64_tr_b16 v[90:91], v119 offset:2816
	v_add_f32_e32 v128, v150, v128
	v_add_f32_e32 v128, v151, v128
	v_add_f32_e32 v136, 0, v128
	ds_read_b64_tr_b16 v[128:129], v119 offset:4608
	s_waitcnt lgkmcnt(0)
	v_mfma_f32_32x32x16_bf16 v[32:47], v[32:35], v[36:39], 0
	v_exp_f32_e32 v142, v53
	v_exp_f32_e32 v143, v54
	v_exp_f32_e32 v144, v55
	v_exp_f32_e32 v145, v56
	v_exp_f32_e32 v146, v57
	v_exp_f32_e32 v147, v58
	v_exp_f32_e32 v149, v59
	v_mfma_f32_32x32x16_bf16 v[32:47], v[92:95], v[88:91], v[32:47]
	ds_read_b64_tr_b16 v[130:131], v119 offset:4864
	ds_read_b64_tr_b16 v[88:89], v119 offset:6656
	ds_read_b64_tr_b16 v[90:91], v119 offset:6912
	s_waitcnt vmcnt(2) lgkmcnt(0)
	s_barrier
; #define HALF(PX0, PX1, PY0, PY1, j_, MORE) do { \
;         SBAR(); if (MORE) DMA((j_) + 2); qkt(PX0, PX1, K_lds + SLOT(j_), qr, negm, r32, hi); \
;         finishSM(PY0, PY1, l_reg, pa0, pa1, pa2, pa3); \
;         pv_d0(o, vb0 + SLOT((j_) - 1), pa0, pa1, pa2, pa3); partialSM(PX0); \
;         if (MORE) WBAR(2); else WBAR(0); } while (0)
; __device__ __forceinline__ void attn_body(const bf16* __restrict__ Qb, const bf16* __restrict__ Kh, const bf16* __restrict__ Vh, bf16* __restrict__ Ob, int seq, float m0l2, char* lds, bool pre, bool post) {
;     ...
;     HALF(pA0, pA1, pB0, pB1, j + 1, false);
	v_exp_f32_e32 v150, v60
	v_exp_f32_e32 v151, v61
	s_waitcnt lgkmcnt(0)
	v_mfma_f32_32x32x16_bf16 v[32:47], v[80:83], v[128:131], v[32:47]
	v_mfma_f32_32x32x16_bf16 v[32:47], v[84:87], v[88:91], v[32:47]
	ds_read_b128 v[128:131], v120 offset:49152
	ds_read_b128 v[48:51], v121 offset:49152
	v_exp_f32_e32 v154, v71
	v_exp_f32_e32 v155, v72
	v_exp_f32_e32 v156, v73
	v_exp_f32_e32 v157, v74
	s_waitcnt lgkmcnt(0)
	v_mfma_f32_32x32x16_bf16 v[80:95], v[48:51], v[108:111], v[0:15]
	v_exp_f32_e32 v158, v75
	v_exp_f32_e32 v159, v76
	v_exp_f32_e32 v162, v77
	v_exp_f32_e32 v163, v78
	v_exp_f32_e32 v79, v79
	v_mfma_f32_32x32x16_bf16 v[48:63], v[128:131], v[108:111], v[0:15]
	ds_read_b128 v[128:131], v122 offset:49152
	ds_read_b128 v[132:135], v123 offset:49152
	s_waitcnt lgkmcnt(0)
	v_mfma_f32_32x32x16_bf16 v[48:63], v[128:131], v[104:107], v[48:63]
	v_mfma_f32_32x32x16_bf16 v[80:95], v[132:135], v[104:107], v[80:95]
	ds_read_b128 v[128:131], v124 offset:49152
	ds_read_b128 v[132:135], v125 offset:49152
	s_waitcnt lgkmcnt(0)
	v_mfma_f32_32x32x16_bf16 v[48:63], v[128:131], v[100:103], v[48:63]
	v_mfma_f32_32x32x16_bf16 v[80:95], v[132:135], v[100:103], v[80:95]
	ds_read_b128 v[128:131], v126 offset:49152
	ds_read_b128 v[132:135], v127 offset:49152
	s_waitcnt lgkmcnt(0)
	v_mfma_f32_32x32x16_bf16 v[48:63], v[128:131], v[96:99], v[48:63]
	v_exp_f32_e32 v129, v64
	v_add_f32_e32 v64, v137, v138
	v_add_f32_e32 v64, v139, v64
	v_add_f32_e32 v64, v140, v64
	v_add_f32_e32 v64, v141, v64
	v_add_f32_e32 v64, v142, v64
	v_add_f32_e32 v64, v143, v64
	v_add_f32_e32 v64, v144, v64
	v_add_f32_e32 v64, v145, v64
	v_add_f32_e32 v64, v146, v64
	v_add_f32_e32 v64, v147, v64
	v_add_f32_e32 v64, v149, v64
	v_add_f32_e32 v64, v150, v64
	v_exp_f32_e32 v130, v65
	v_add_f32_e32 v64, v151, v64
	v_exp_f32_e32 v131, v66
	v_add_f32_e32 v64, v152, v64
	v_mfma_f32_32x32x16_bf16 v[80:95], v[132:135], v[96:99], v[80:95]
	v_exp_f32_e32 v132, v67
	v_add_f32_e32 v64, v153, v64
	v_exp_f32_e32 v133, v68
	v_add_f32_e32 v64, v129, v64
	v_exp_f32_e32 v134, v69
	v_add_f32_e32 v64, v130, v64
	v_exp_f32_e32 v135, v70
	v_add_f32_e32 v64, v131, v64
	v_add_f32_e32 v64, v132, v64
	v_add_f32_e32 v64, v133, v64
	v_add_f32_e32 v64, v134, v64
	v_add_f32_e32 v64, v135, v64
	v_add_f32_e32 v64, v154, v64
	v_add_f32_e32 v64, v155, v64
	v_add_f32_e32 v64, v156, v64
	v_add_f32_e32 v64, v157, v64
	v_add_f32_e32 v64, v158, v64
	v_add_f32_e32 v64, v159, v64
	v_add_f32_e32 v64, v162, v64
	v_add_f32_e32 v64, v163, v64
	v_add_f32_e32 v64, v79, v64
	v_add_f32_e32 v128, v136, v64
	v_cvt_pk_bf16_f32 v64, v137, v138
	v_cvt_pk_bf16_f32 v65, v139, v140
	v_cvt_pk_bf16_f32 v66, v141, v142
	v_cvt_pk_bf16_f32 v67, v143, v144
	v_cvt_pk_bf16_f32 v68, v145, v146
	v_cvt_pk_bf16_f32 v69, v147, v149
	v_cvt_pk_bf16_f32 v70, v150, v151
	v_cvt_pk_bf16_f32 v71, v152, v153
	v_cvt_pk_bf16_f32 v72, v129, v130
	v_cvt_pk_bf16_f32 v73, v131, v132
	v_cvt_pk_bf16_f32 v74, v133, v134
	v_cvt_pk_bf16_f32 v75, v135, v154
	v_cvt_pk_bf16_f32 v76, v155, v156
	v_cvt_pk_bf16_f32 v77, v157, v158
	v_cvt_pk_bf16_f32 v78, v159, v162
	v_cvt_pk_bf16_f32 v79, v163, v79
	ds_read_b64_tr_b16 v[130:131], v119 offset:8192
	ds_read_b64_tr_b16 v[132:133], v119 offset:8448
	ds_read_b64_tr_b16 v[134:135], v119 offset:10240
	ds_read_b64_tr_b16 v[136:137], v119 offset:10496
	ds_read_b64_tr_b16 v[138:139], v119 offset:12288
	ds_read_b64_tr_b16 v[140:141], v119 offset:12544
	ds_read_b64_tr_b16 v[142:143], v119 offset:14336
	ds_read_b64_tr_b16 v[144:145], v119 offset:14592
	s_waitcnt lgkmcnt(0)
	v_mfma_f32_32x32x16_bf16 v[16:31], v[64:67], v[130:133], v[16:31]
	v_exp_f32_e32 v129, v80
	v_exp_f32_e32 v88, v88
	v_exp_f32_e32 v89, v89
	v_exp_f32_e32 v90, v90
	v_exp_f32_e32 v91, v91
	v_exp_f32_e32 v92, v92
	v_exp_f32_e32 v93, v93
	v_mfma_f32_32x32x16_bf16 v[16:31], v[68:71], v[134:137], v[16:31]
	v_exp_f32_e32 v94, v94
	v_exp_f32_e32 v95, v95
	v_mfma_f32_32x32x16_bf16 v[16:31], v[72:75], v[138:141], v[16:31]
	v_mfma_f32_32x32x16_bf16 v[16:31], v[76:79], v[142:145], v[16:31]
	ds_read_b64_tr_b16 v[130:131], v119 offset:8704
	ds_read_b64_tr_b16 v[132:133], v119 offset:8960
	ds_read_b64_tr_b16 v[134:135], v119 offset:10752
	ds_read_b64_tr_b16 v[136:137], v119 offset:11008
	ds_read_b64_tr_b16 v[138:139], v119 offset:12800
	ds_read_b64_tr_b16 v[140:141], v119 offset:13056
	ds_read_b64_tr_b16 v[142:143], v119 offset:14848
	ds_read_b64_tr_b16 v[144:145], v119 offset:15104
	s_waitcnt vmcnt(0) lgkmcnt(0)
	s_barrier
; #define SBAR() __builtin_amdgcn_sched_barrier(0)
; __device__ __forceinline__ void attn_body(const bf16* __restrict__ Qb, const bf16* __restrict__ Kh, const bf16* __restrict__ Vh, bf16* __restrict__ Ob, int seq, float m0l2, char* lds, bool pre, bool post) {
;     ...
;     SBAR(); qkt(pB0, pB1, K_lds + SLOT(NT - 1), qr, negm, r32, hi);
;     finishSM(pA0, pA1, l_reg, pa0, pa1, pa2, pa3); SBAR();
;     pv_d0(o, vb0 + SLOT(NT - 2), pa0, pa1, pa2, pa3); partialSM(pB0);
	s_waitcnt lgkmcnt(0)
	v_mfma_f32_32x32x16_bf16 v[32:47], v[64:67], v[130:133], v[32:47]
	v_exp_f32_e32 v130, v81
	v_exp_f32_e32 v131, v82
	v_exp_f32_e32 v132, v83
	v_exp_f32_e32 v133, v84
	v_mfma_f32_32x32x16_bf16 v[32:47], v[68:71], v[134:137], v[32:47]
	v_exp_f32_e32 v134, v85
	v_exp_f32_e32 v135, v86
	v_exp_f32_e32 v136, v87
	v_mfma_f32_32x32x16_bf16 v[32:47], v[72:75], v[138:141], v[32:47]
	v_mfma_f32_32x32x16_bf16 v[32:47], v[76:79], v[142:145], v[32:47]
	ds_read_b128 v[80:83], v120 offset:57344
	ds_read_b128 v[84:87], v121 offset:57344
	v_exp_f32_e32 v63, v63
	s_waitcnt lgkmcnt(0)
	v_mfma_f32_32x32x16_bf16 v[64:79], v[84:87], v[108:111], v[0:15]
	v_mfma_f32_32x32x16_bf16 v[0:15], v[80:83], v[108:111], v[0:15]
	ds_read_b128 v[80:83], v122 offset:57344
	ds_read_b128 v[84:87], v123 offset:57344
	s_waitcnt lgkmcnt(0)
	v_mfma_f32_32x32x16_bf16 v[0:15], v[80:83], v[104:107], v[0:15]
	v_mfma_f32_32x32x16_bf16 v[64:79], v[84:87], v[104:107], v[64:79]
	ds_read_b128 v[80:83], v124 offset:57344
	ds_read_b128 v[84:87], v125 offset:57344
	s_waitcnt lgkmcnt(0)
	v_mfma_f32_32x32x16_bf16 v[0:15], v[80:83], v[100:103], v[0:15]
	v_mfma_f32_32x32x16_bf16 v[64:79], v[84:87], v[100:103], v[64:79]
	ds_read_b128 v[80:83], v126 offset:57344
	ds_read_b128 v[84:87], v127 offset:57344
	v_exp_f32_e32 v100, v60
	v_exp_f32_e32 v101, v61
	v_exp_f32_e32 v102, v62
	s_waitcnt lgkmcnt(0)
	v_mfma_f32_32x32x16_bf16 v[0:15], v[80:83], v[96:99], v[0:15]
	v_exp_f32_e32 v80, v48
	v_add_f32_e32 v48, v129, v130
	v_add_f32_e32 v48, v131, v48
	v_add_f32_e32 v48, v132, v48
	v_add_f32_e32 v48, v133, v48
	v_add_f32_e32 v48, v134, v48
	v_add_f32_e32 v48, v135, v48
	v_add_f32_e32 v48, v136, v48
	v_add_f32_e32 v48, v88, v48
	v_add_f32_e32 v48, v89, v48
	v_add_f32_e32 v48, v90, v48
	v_add_f32_e32 v48, v91, v48
	v_add_f32_e32 v48, v92, v48
	v_exp_f32_e32 v81, v49
	v_add_f32_e32 v48, v93, v48
	v_exp_f32_e32 v82, v50
	v_add_f32_e32 v48, v94, v48
	v_exp_f32_e32 v83, v51
	v_add_f32_e32 v48, v95, v48
	v_mfma_f32_32x32x16_bf16 v[64:79], v[84:87], v[96:99], v[64:79]
	v_exp_f32_e32 v84, v52
	v_add_f32_e32 v48, v80, v48
	v_exp_f32_e32 v85, v53
	v_add_f32_e32 v48, v81, v48
	v_exp_f32_e32 v86, v54
	v_add_f32_e32 v48, v82, v48
	v_exp_f32_e32 v87, v55
	v_add_f32_e32 v48, v83, v48
	v_exp_f32_e32 v96, v56
	v_add_f32_e32 v48, v84, v48
	v_exp_f32_e32 v97, v57
	v_add_f32_e32 v48, v85, v48
	v_exp_f32_e32 v98, v58
	v_add_f32_e32 v48, v86, v48
	v_exp_f32_e32 v99, v59
	v_add_f32_e32 v48, v87, v48
	v_add_f32_e32 v48, v96, v48
	v_add_f32_e32 v48, v97, v48
	v_add_f32_e32 v48, v98, v48
	v_add_f32_e32 v48, v99, v48
	v_add_f32_e32 v48, v100, v48
	v_add_f32_e32 v48, v101, v48
	v_add_f32_e32 v48, v102, v48
	v_add_f32_e32 v48, v63, v48
	v_add_f32_e32 v103, v128, v48
	v_cvt_pk_bf16_f32 v48, v129, v130
	v_cvt_pk_bf16_f32 v49, v131, v132
	v_cvt_pk_bf16_f32 v50, v133, v134
	v_cvt_pk_bf16_f32 v51, v135, v136
	v_cvt_pk_bf16_f32 v52, v88, v89
	v_cvt_pk_bf16_f32 v53, v90, v91
	v_cvt_pk_bf16_f32 v54, v92, v93
	v_cvt_pk_bf16_f32 v55, v94, v95
	v_cvt_pk_bf16_f32 v56, v80, v81
	v_cvt_pk_bf16_f32 v57, v82, v83
	v_cvt_pk_bf16_f32 v58, v84, v85
	v_cvt_pk_bf16_f32 v59, v86, v87
	v_cvt_pk_bf16_f32 v60, v96, v97
	v_cvt_pk_bf16_f32 v61, v98, v99
	v_cvt_pk_bf16_f32 v62, v100, v101
	v_cvt_pk_bf16_f32 v63, v102, v63
	ds_read_b64_tr_b16 v[80:81], v119 offset:16384
	ds_read_b64_tr_b16 v[82:83], v119 offset:16640
	ds_read_b64_tr_b16 v[84:85], v119 offset:18432
	ds_read_b64_tr_b16 v[86:87], v119 offset:18688
	ds_read_b64_tr_b16 v[88:89], v119 offset:20480
	ds_read_b64_tr_b16 v[90:91], v119 offset:20736
	ds_read_b64_tr_b16 v[92:93], v119 offset:22528
	ds_read_b64_tr_b16 v[94:95], v119 offset:22784
	s_waitcnt lgkmcnt(0)
	v_mfma_f32_32x32x16_bf16 v[16:31], v[48:51], v[80:83], v[16:31]
	v_exp_f32_e32 v1, v1
	v_exp_f32_e32 v14, v14
	v_exp_f32_e32 v15, v15
	v_mfma_f32_32x32x16_bf16 v[16:31], v[52:55], v[84:87], v[16:31]
	v_mfma_f32_32x32x16_bf16 v[16:31], v[56:59], v[88:91], v[16:31]
	v_mfma_f32_32x32x16_bf16 v[16:31], v[60:63], v[92:95], v[16:31]
	ds_read_b64_tr_b16 v[80:81], v119 offset:16896
	ds_read_b64_tr_b16 v[82:83], v119 offset:17152
	ds_read_b64_tr_b16 v[84:85], v119 offset:18944
	ds_read_b64_tr_b16 v[86:87], v119 offset:19200
	ds_read_b64_tr_b16 v[88:89], v119 offset:20992
	ds_read_b64_tr_b16 v[90:91], v119 offset:21248
	ds_read_b64_tr_b16 v[92:93], v119 offset:23040
	ds_read_b64_tr_b16 v[94:95], v119 offset:23296
	s_waitcnt lgkmcnt(0)
; #define SBAR() __builtin_amdgcn_sched_barrier(0)
; __device__ __forceinline__ int crow(int r, int hi) { return (r & 3) + 8 * (r >> 2) + 4 * hi; }
; __device__ __forceinline__ void attn_body(const bf16* __restrict__ Qb, const bf16* __restrict__ Kh, const bf16* __restrict__ Vh, bf16* __restrict__ Ob, int seq, float m0l2, char* lds, bool pre, bool post) {
;     ...
;     finishSM(pA0, pA1, l_reg, pa0, pa1, pa2, pa3); SBAR();
;     pv_d0(o, vb0 + SLOT(NT - 2), pa0, pa1, pa2, pa3); partialSM(pB0);
;     finishSM(pB0, pB1, l_reg, pa0, pa1, pa2, pa3); SBAR();
;     pv_d0(o, vb0 + SLOT(NT - 1), pa0, pa1, pa2, pa3);
;     { auto rr = __builtin_amdgcn_permlane32_swap(__float_as_uint(l_reg), __float_as_uint(l_reg), false, false); l_reg = __uint_as_float(rr[0]) + __uint_as_float(rr[1]); }
;     if (hi == 0) li_l[r32] = l_reg; asm volatile("s_waitcnt lgkmcnt(0)" ::: "memory");
;     float rli[16];
; #pragma unroll
;     for (int r = 0; r < 16; ++r) rli[r] = __builtin_amdgcn_rcpf(li_l[crow(r, hi)]);
	v_mfma_f32_32x32x16_bf16 v[32:47], v[48:51], v[80:83], v[32:47]
	v_exp_f32_e32 v48, v64
	v_exp_f32_e32 v49, v65
	v_exp_f32_e32 v50, v66
	v_exp_f32_e32 v51, v67
	v_exp_f32_e32 v64, v0
	v_add_f32_e32 v0, v48, v49
	v_add_f32_e32 v0, v50, v0
	v_mfma_f32_32x32x16_bf16 v[32:47], v[52:55], v[84:87], v[32:47]
	v_exp_f32_e32 v52, v68
	v_exp_f32_e32 v53, v69
	v_exp_f32_e32 v54, v70
	v_exp_f32_e32 v55, v71
	v_add_f32_e32 v0, v51, v0
	v_add_f32_e32 v0, v52, v0
	v_add_f32_e32 v0, v53, v0
	v_mfma_f32_32x32x16_bf16 v[32:47], v[56:59], v[88:91], v[32:47]
	v_exp_f32_e32 v56, v72
	v_exp_f32_e32 v57, v73
	v_exp_f32_e32 v58, v74
	v_add_f32_e32 v0, v54, v0
	v_exp_f32_e32 v59, v75
	v_add_f32_e32 v0, v55, v0
	v_add_f32_e32 v0, v56, v0
	v_mfma_f32_32x32x16_bf16 v[32:47], v[60:63], v[92:95], v[32:47]
	v_exp_f32_e32 v60, v76
	v_exp_f32_e32 v61, v77
	v_add_f32_e32 v0, v57, v0
	v_exp_f32_e32 v62, v78
	v_add_f32_e32 v0, v58, v0
	v_exp_f32_e32 v63, v79
	v_add_f32_e32 v0, v59, v0
	v_add_f32_e32 v0, v60, v0
	v_add_f32_e32 v0, v61, v0
	v_exp_f32_e32 v65, v2
	v_add_f32_e32 v0, v62, v0
	v_exp_f32_e32 v66, v3
	v_add_f32_e32 v0, v63, v0
	v_exp_f32_e32 v67, v4
	v_add_f32_e32 v0, v64, v0
	v_exp_f32_e32 v68, v5
	v_add_f32_e32 v0, v1, v0
	v_exp_f32_e32 v69, v6
	v_add_f32_e32 v0, v65, v0
	v_exp_f32_e32 v70, v7
	v_add_f32_e32 v0, v66, v0
	v_exp_f32_e32 v71, v8
	v_add_f32_e32 v0, v67, v0
	v_exp_f32_e32 v72, v9
	v_add_f32_e32 v0, v68, v0
	v_exp_f32_e32 v73, v10
	v_add_f32_e32 v0, v69, v0
	v_exp_f32_e32 v74, v11
	v_add_f32_e32 v0, v70, v0
	v_exp_f32_e32 v75, v12
	v_add_f32_e32 v0, v71, v0
	v_exp_f32_e32 v76, v13
	v_add_f32_e32 v0, v72, v0
	v_add_f32_e32 v0, v73, v0
	v_add_f32_e32 v0, v74, v0
	v_add_f32_e32 v0, v75, v0
	v_add_f32_e32 v0, v76, v0
	v_add_f32_e32 v0, v14, v0
	v_add_f32_e32 v0, v15, v0
	v_add_f32_e32 v0, v103, v0
	v_cvt_pk_bf16_f32 v2, v48, v49
	v_cvt_pk_bf16_f32 v3, v50, v51
	v_cvt_pk_bf16_f32 v4, v52, v53
	v_cvt_pk_bf16_f32 v5, v54, v55
	v_cvt_pk_bf16_f32 v6, v56, v57
	v_cvt_pk_bf16_f32 v7, v58, v59
	v_cvt_pk_bf16_f32 v8, v60, v61
	v_cvt_pk_bf16_f32 v9, v62, v63
	v_cvt_pk_bf16_f32 v10, v64, v1
	v_cvt_pk_bf16_f32 v11, v65, v66
	v_cvt_pk_bf16_f32 v12, v67, v68
	v_cvt_pk_bf16_f32 v13, v69, v70
	v_cvt_pk_bf16_f32 v48, v71, v72
	v_cvt_pk_bf16_f32 v49, v73, v74
	v_cvt_pk_bf16_f32 v50, v75, v76
	v_cvt_pk_bf16_f32 v51, v14, v15
	ds_read_b64_tr_b16 v[52:53], v119 offset:24576
	ds_read_b64_tr_b16 v[54:55], v119 offset:24832
	v_mov_b32_e32 v1, v0
	s_nop 1
	v_permlane32_swap_b32_e32 v0, v1
	v_cmp_gt_u32_e32 vcc, 32, v115
	s_waitcnt lgkmcnt(0)
	v_mfma_f32_32x32x16_bf16 v[16:31], v[2:5], v[52:55], v[16:31]
	ds_read_b64_tr_b16 v[52:53], v119 offset:26624
	ds_read_b64_tr_b16 v[54:55], v119 offset:26880
	s_waitcnt lgkmcnt(0)
	v_mfma_f32_32x32x16_bf16 v[16:31], v[6:9], v[52:55], v[16:31]
	ds_read_b64_tr_b16 v[52:53], v119 offset:28672
	ds_read_b64_tr_b16 v[54:55], v119 offset:28928
	s_waitcnt lgkmcnt(0)
	v_mfma_f32_32x32x16_bf16 v[16:31], v[10:13], v[52:55], v[16:31]
	ds_read_b64_tr_b16 v[52:53], v119 offset:30720
	ds_read_b64_tr_b16 v[54:55], v119 offset:30976
	s_waitcnt lgkmcnt(0)
	v_mfma_f32_32x32x16_bf16 v[16:31], v[48:51], v[52:55], v[16:31]
	ds_read_b64_tr_b16 v[52:53], v119 offset:25088
	ds_read_b64_tr_b16 v[54:55], v119 offset:25344
	s_waitcnt lgkmcnt(0)
	v_mfma_f32_32x32x16_bf16 v[32:47], v[2:5], v[52:55], v[32:47]
	ds_read_b64_tr_b16 v[2:3], v119 offset:27136
	ds_read_b64_tr_b16 v[4:5], v119 offset:27392
	s_waitcnt lgkmcnt(0)
	v_mfma_f32_32x32x16_bf16 v[32:47], v[6:9], v[2:5], v[32:47]
	ds_read_b64_tr_b16 v[2:3], v119 offset:29184
	ds_read_b64_tr_b16 v[4:5], v119 offset:29440
	s_waitcnt lgkmcnt(0)
	v_mfma_f32_32x32x16_bf16 v[32:47], v[10:13], v[2:5], v[32:47]
	ds_read_b64_tr_b16 v[2:3], v119 offset:31232
	ds_read_b64_tr_b16 v[4:5], v119 offset:31488
	s_waitcnt lgkmcnt(0)
	v_mfma_f32_32x32x16_bf16 v[32:47], v[48:51], v[2:5], v[32:47]
	s_and_saveexec_b64 s[6:7], vcc
	v_add_f32_e32 v0, v0, v1
	v_lshl_add_u32 v1, v116, 2, v113
	ds_write_b32 v1, v0
	s_or_b64 exec, exec, s[6:7]
	s_waitcnt lgkmcnt(0)
	v_add_u32_e32 v8, v113, v160
	ds_read_b128 v[0:3], v8
	ds_read_b128 v[4:7], v8 offset:32
	v_readlane_b32 s3, v254, 7
	s_add_u32 s3, s16, s3
	s_addc_u32 s7, s17, 0
	s_waitcnt lgkmcnt(0)
; __device__ __forceinline__ unsigned f2bf(float f) { unsigned u = __builtin_bit_cast(unsigned, f); return (u + 0x7fffu + ((u >> 16) & 1u)) >> 16; }
; __device__ __forceinline__ int crow(int r, int hi) { return (r & 3) + 8 * (r >> 2) + 4 * hi; }
; __device__ __forceinline__ void attn_body(const bf16* __restrict__ Qb, const bf16* __restrict__ Kh, const bf16* __restrict__ Vh, bf16* __restrict__ Ob, int seq, float m0l2, char* lds, bool pre, bool post) {
;     ...
;     for (int r = 0; r < 16; ++r) rli[r] = __builtin_amdgcn_rcpf(li_l[crow(r, hi)]);
;     bf16* Ow = Ob + (long)(wid * QBLK) * LDO;
;     {
;         bf16* stg = (bf16*)(lds + OFF_OST) + wid * 2048;
; #pragma unroll
;         for (int r = 0; r < 16; ++r) { const int orow = crow(r, hi);
; #pragma unroll
;             for (int d0 = 0; d0 < 2; ++d0) stg[orow * 64 + d0 * 32 + r32] = (bf16)f2bf(o[d0][r] * rli[r]); }
;         asm volatile("s_waitcnt lgkmcnt(0)" ::: "memory");
; #pragma unroll
;         for (int i = 0; i < 4; ++i) { const int row = i * 8 + (lane >> 3), ch = lane & 7; const u32x4 v = *(const u32x4*)(stg + row * 64 + ch * 8); *(u32x4*)(Ow + (long)row * LDO + ch * 8) = v; }
;     }
;     asm volatile("s_waitcnt vmcnt(0)" ::: "memory");
;     __syncthreads();
	v_rcp_f32_e32 v9, v0
	v_readlane_b32 s8, v254, 61
	s_add_u32 s6, s3, s8
	v_readlane_b32 s3, v255, 1
	v_lshlrev_b32_e32 v51, 9, v118
	v_lshlrev_b32_e32 v52, 1, v116
	v_lshl_add_u32 v50, v117, 12, s3
	v_mul_f32_e32 v16, v16, v9
	v_rcp_f32_e32 v10, v1
	v_add3_u32 v51, v50, v51, v52
	v_bfe_u32 v52, v16, 16, 1
	v_add3_u32 v16, v16, v52, s56
	v_mul_f32_e32 v9, v32, v9
	ds_write_b16_d16_hi v51, v16
	v_bfe_u32 v16, v9, 16, 1
	v_add3_u32 v9, v9, v16, s56
	ds_write_b16_d16_hi v51, v9 offset:64
	v_mul_f32_e32 v9, v17, v10
	v_bfe_u32 v16, v9, 16, 1
	v_rcp_f32_e32 v11, v2
	v_add3_u32 v9, v9, v16, s56
	ds_write_b16_d16_hi v51, v9 offset:128
	v_mul_f32_e32 v9, v33, v10
	v_bfe_u32 v10, v9, 16, 1
	v_add3_u32 v9, v9, v10, s56
	ds_write_b16_d16_hi v51, v9 offset:192
	v_mul_f32_e32 v9, v18, v11
	v_bfe_u32 v10, v9, 16, 1
	v_rcp_f32_e32 v12, v3
	v_add3_u32 v9, v9, v10, s56
	ds_write_b16_d16_hi v51, v9 offset:256
	v_mul_f32_e32 v9, v34, v11
	v_bfe_u32 v10, v9, 16, 1
	v_add3_u32 v9, v9, v10, s56
	ds_write_b16_d16_hi v51, v9 offset:320
	v_mul_f32_e32 v9, v19, v12
	v_bfe_u32 v10, v9, 16, 1
	v_rcp_f32_e32 v13, v4
	v_add3_u32 v9, v9, v10, s56
	ds_write_b16_d16_hi v51, v9 offset:384
	v_mul_f32_e32 v9, v35, v12
	v_bfe_u32 v10, v9, 16, 1
	v_add3_u32 v9, v9, v10, s56
	ds_write_b16_d16_hi v51, v9 offset:448
	v_mul_f32_e32 v9, v20, v13
	v_bfe_u32 v10, v9, 16, 1
	v_rcp_f32_e32 v14, v5
	v_add3_u32 v9, v9, v10, s56
	ds_write_b16_d16_hi v51, v9 offset:1024
	v_mul_f32_e32 v9, v36, v13
	v_bfe_u32 v10, v9, 16, 1
	v_add3_u32 v9, v9, v10, s56
	ds_write_b16_d16_hi v51, v9 offset:1088
	v_mul_f32_e32 v9, v21, v14
	v_bfe_u32 v10, v9, 16, 1
	v_rcp_f32_e32 v15, v6
	v_add3_u32 v9, v9, v10, s56
	ds_write_b16_d16_hi v51, v9 offset:1152
	v_mul_f32_e32 v9, v37, v14
	v_bfe_u32 v10, v9, 16, 1
	v_add3_u32 v9, v9, v10, s56
	ds_write_b16_d16_hi v51, v9 offset:1216
	v_mul_f32_e32 v9, v22, v15
	v_bfe_u32 v10, v9, 16, 1
	v_rcp_f32_e32 v48, v7
	v_add3_u32 v9, v9, v10, s56
	ds_read_b128 v[0:3], v8 offset:64
	ds_read_b128 v[4:7], v8 offset:96
	ds_write_b16_d16_hi v51, v9 offset:1280
	v_mul_f32_e32 v9, v38, v15
	v_bfe_u32 v10, v9, 16, 1
	v_add3_u32 v9, v9, v10, s56
	ds_write_b16_d16_hi v51, v9 offset:1344
	v_mul_f32_e32 v9, v23, v48
	v_bfe_u32 v10, v9, 16, 1
	s_waitcnt lgkmcnt(0)
	v_rcp_f32_e32 v8, v0
	v_add3_u32 v9, v9, v10, s56
	ds_write_b16_d16_hi v51, v9 offset:1408
	v_mul_f32_e32 v9, v39, v48
	v_bfe_u32 v10, v9, 16, 1
	v_add3_u32 v9, v9, v10, s56
	ds_write_b16_d16_hi v51, v9 offset:1472
	v_mul_f32_e32 v9, v24, v8
	v_rcp_f32_e32 v49, v1
	v_bfe_u32 v10, v9, 16, 1
	v_add3_u32 v9, v9, v10, s56
	v_mul_f32_e32 v8, v40, v8
	ds_write_b16_d16_hi v51, v9 offset:2048
	v_bfe_u32 v9, v8, 16, 1
	v_add3_u32 v8, v8, v9, s56
	ds_write_b16_d16_hi v51, v8 offset:2112
	v_mul_f32_e32 v8, v25, v49
	v_bfe_u32 v9, v8, 16, 1
	v_rcp_f32_e32 v2, v2
	v_add3_u32 v8, v8, v9, s56
	ds_write_b16_d16_hi v51, v8 offset:2176
	v_mul_f32_e32 v8, v41, v49
	v_bfe_u32 v9, v8, 16, 1
	v_add3_u32 v8, v8, v9, s56
	ds_write_b16_d16_hi v51, v8 offset:2240
	v_mul_f32_e32 v8, v26, v2
	v_rcp_f32_e32 v3, v3
	v_bfe_u32 v9, v8, 16, 1
	v_add3_u32 v8, v8, v9, s56
	v_mul_f32_e32 v2, v42, v2
	ds_write_b16_d16_hi v51, v8 offset:2304
	v_bfe_u32 v8, v2, 16, 1
	v_add3_u32 v2, v2, v8, s56
	ds_write_b16_d16_hi v51, v2 offset:2368
	v_mul_f32_e32 v2, v27, v3
	v_bfe_u32 v8, v2, 16, 1
	v_rcp_f32_e32 v4, v4
	v_add3_u32 v2, v2, v8, s56
	ds_write_b16_d16_hi v51, v2 offset:2432
	v_mul_f32_e32 v2, v43, v3
	v_bfe_u32 v3, v2, 16, 1
	v_add3_u32 v2, v2, v3, s56
	ds_write_b16_d16_hi v51, v2 offset:2496
	v_mul_f32_e32 v2, v28, v4
	v_bfe_u32 v3, v2, 16, 1
	v_rcp_f32_e32 v5, v5
	v_add3_u32 v2, v2, v3, s56
	ds_write_b16_d16_hi v51, v2 offset:3072
	v_mul_f32_e32 v2, v44, v4
	v_bfe_u32 v3, v2, 16, 1
	v_add3_u32 v2, v2, v3, s56
	ds_write_b16_d16_hi v51, v2 offset:3136
	v_mul_f32_e32 v2, v29, v5
	v_bfe_u32 v3, v2, 16, 1
	v_rcp_f32_e32 v6, v6
	v_add3_u32 v2, v2, v3, s56
	ds_write_b16_d16_hi v51, v2 offset:3200
	v_mul_f32_e32 v2, v45, v5
	v_bfe_u32 v3, v2, 16, 1
	v_add3_u32 v2, v2, v3, s56
	ds_write_b16_d16_hi v51, v2 offset:3264
	v_mul_f32_e32 v2, v30, v6
	v_bfe_u32 v3, v2, 16, 1
	v_rcp_f32_e32 v7, v7
	v_add3_u32 v2, v2, v3, s56
	ds_write_b16_d16_hi v51, v2 offset:3328
	v_mul_f32_e32 v2, v46, v6
	v_bfe_u32 v3, v2, 16, 1
	v_add3_u32 v2, v2, v3, s56
	ds_write_b16_d16_hi v51, v2 offset:3392
	v_mul_f32_e32 v2, v31, v7
	v_bfe_u32 v3, v2, 16, 1
	v_add3_u32 v2, v2, v3, s56
	ds_write_b16_d16_hi v51, v2 offset:3456
	v_mul_f32_e32 v2, v47, v7
	v_bfe_u32 v3, v2, 16, 1
	v_add3_u32 v2, v2, v3, s56
	v_readlane_b32 s9, v254, 62
	v_ashrrev_i32_e32 v113, 31, v112
	ds_write_b16_d16_hi v51, v2 offset:3520
	v_lshlrev_b32_e32 v2, 4, v114
	s_addc_u32 s7, s7, s9
	v_lshlrev_b64 v[0:1], 11, v[112:113]
	v_and_b32_e32 v160, 0x70, v2
	v_lshl_add_u64 v[0:1], s[6:7], 0, v[0:1]
	v_lshrrev_b32_e32 v12, 3, v115
	v_add_u32_e32 v13, v50, v160
	s_waitcnt lgkmcnt(0)
	v_lshl_add_u64 v[8:9], v[0:1], 0, v[160:161]
	v_lshl_add_u32 v0, v12, 7, v13
	v_or_b32_e32 v14, 8, v12
	ds_read_b128 v[0:3], v0
	v_lshl_add_u32 v4, v14, 7, v13
	ds_read_b128 v[4:7], v4
	v_lshlrev_b32_e32 v160, 11, v12
	v_lshl_add_u64 v[10:11], v[8:9], 0, v[160:161]
	v_lshlrev_b32_e32 v160, 11, v14
	s_waitcnt lgkmcnt(0)
	global_store_dwordx4 v[10:11], v[0:3], off
	s_nop 1
	v_lshl_add_u64 v[0:1], v[8:9], 0, v[160:161]
	global_store_dwordx4 v[0:1], v[4:7], off
	s_nop 1
	v_or_b32_e32 v4, 16, v12
	v_lshl_add_u32 v0, v4, 7, v13
	v_or_b32_e32 v12, 24, v12
	ds_read_b128 v[0:3], v0
	v_lshlrev_b32_e32 v160, 11, v4
	v_lshl_add_u32 v4, v12, 7, v13
	ds_read_b128 v[4:7], v4
	v_lshl_add_u64 v[10:11], v[8:9], 0, v[160:161]
	v_lshlrev_b32_e32 v160, 11, v12
	s_waitcnt lgkmcnt(0)
	global_store_dwordx4 v[10:11], v[0:3], off
	s_nop 1
	v_lshl_add_u64 v[0:1], v[8:9], 0, v[160:161]
	global_store_dwordx4 v[0:1], v[4:7], off
	s_waitcnt vmcnt(0)
	s_waitcnt vmcnt(0)
	s_barrier
